# conv/f1/FFT output stores sc1 (write-through, so the seam writeback has less to flush)
# speedup vs baseline: 1.0133x; 1.0133x over previous
.LBB0_227:
	s_lshl_b32 s0, s2, 4
	v_or_b32_e32 v86, s0, v102
	v_mad_i64_i32 v[24:25], s[18:19], v86, s6, v[56:57]
	v_add_co_u32_e32 v26, vcc, 0x1000, v24
	global_load_dwordx4 v[52:55], v[24:25], off
	global_load_dwordx4 v[48:51], v[24:25], off offset:3584
	v_addc_co_u32_e32 v27, vcc, 0, v25, vcc
	global_load_dwordx4 v[44:47], v[26:27], off offset:3072
	v_add_co_u32_e32 v26, vcc, s15, v24
	s_bfe_i32 s0, s2, 0x1001b
	s_nop 0
	v_addc_co_u32_e32 v27, vcc, 0, v25, vcc
	global_load_dwordx4 v[40:43], v[26:27], off offset:2560
	v_add_co_u32_e32 v26, vcc, s35, v24
	v_ashrrev_i32_e32 v87, 31, v86
	s_nop 0
	v_addc_co_u32_e32 v27, vcc, 0, v25, vcc
	global_load_dwordx4 v[36:39], v[26:27], off offset:2048
	v_add_co_u32_e32 v26, vcc, s44, v24
	s_lshr_b32 s0, s0, 19
	s_nop 0
	v_addc_co_u32_e32 v27, vcc, 0, v25, vcc
	v_lshlrev_b64 v[84:85], 11, v[86:87]
	global_load_dwordx4 v[32:35], v[26:27], off offset:1536
	v_add_co_u32_e32 v26, vcc, s46, v24
	v_add_u32_e32 v87, s0, v86
	s_nop 0
	v_addc_co_u32_e32 v27, vcc, 0, v25, vcc
	v_and_b32_e32 v87, 0xffffe000, v87
	v_add_co_u32_e32 v24, vcc, s45, v24
	v_sub_u32_e32 v87, v86, v87
	s_nop 0
	v_addc_co_u32_e32 v25, vcc, 0, v25, vcc
	v_add_u32_e32 v217, -1, v87
	v_cmp_gt_u32_e32 vcc, s15, v217
	global_load_dwordx4 v[28:31], v[26:27], off offset:1024
	v_lshl_add_u64 v[84:85], v[58:59], 0, v[84:85]
	global_load_dwordx4 v[24:27], v[24:25], off offset:512
	s_nop 0
	v_add_u32_e32 v88, -1, v86
	v_max_i32_e32 v88, 0, v88
	v_min_u32_e32 v88, 0xffff, v88
	v_mul_u32_u24_e32 v208, 0xe00, v88
	v_lshl_add_u64 v[92:93], v[56:57], 0, v[208:209]
	global_load_dwordx4 v[88:91], v[92:93], off offset:512
	s_nop 0
	global_load_dwordx4 v[92:95], v[92:93], off offset:1024
	v_add_u32_e32 v218, 0, v86
	v_max_i32_e32 v218, 0, v218
	v_min_u32_e32 v218, 0xffff, v218
	v_mul_u32_u24_e32 v208, 0xe00, v218
	v_lshl_add_u64 v[222:223], v[56:57], 0, v[208:209]
	global_load_dwordx4 v[218:221], v[222:223], off offset:512
	s_nop 0
	global_load_dwordx4 v[222:225], v[222:223], off offset:1024
	v_add_u32_e32 v226, 1, v86
	v_max_i32_e32 v226, 0, v226
	v_min_u32_e32 v226, 0xffff, v226
	v_mul_u32_u24_e32 v208, 0xe00, v226
	v_lshl_add_u64 v[230:231], v[56:57], 0, v[208:209]
	global_load_dwordx4 v[226:229], v[230:231], off offset:512
	s_nop 0
	global_load_dwordx4 v[230:233], v[230:231], off offset:1024
	v_add_u32_e32 v234, 2, v86
	v_max_i32_e32 v234, 0, v234
	v_min_u32_e32 v234, 0xffff, v234
	v_mul_u32_u24_e32 v208, 0xe00, v234
	v_lshl_add_u64 v[238:239], v[56:57], 0, v[208:209]
	global_load_dwordx4 v[234:237], v[238:239], off offset:512
	s_nop 0
	global_load_dwordx4 v[238:241], v[238:239], off offset:1024
	s_add_i32 s2, s2, s3
	s_cmpk_lt_i32 s2, 0x1000
	s_waitcnt vmcnt(6)
	v_cndmask_b32_e32 v97, 0, v88, vcc
	v_cndmask_b32_e32 v149, 0, v93, vcc
	v_cndmask_b32_e32 v98, 0, v92, vcc
	v_cndmask_b32_e32 v141, 0, v91, vcc
	v_cndmask_b32_e32 v143, 0, v90, vcc
	v_cndmask_b32_e32 v96, 0, v89, vcc
	v_cndmask_b32_e32 v145, 0, v95, vcc
	v_cndmask_b32_e32 v147, 0, v94, vcc
	v_add_u32_e32 v88, 3, v86
	v_max_i32_e32 v88, 0, v88
	v_min_u32_e32 v88, 0xffff, v88
	v_mul_u32_u24_e32 v208, 0xe00, v88
	v_lshl_add_u64 v[92:93], v[56:57], 0, v[208:209]
	global_load_dwordx4 v[88:91], v[92:93], off offset:512
	s_nop 0
	global_load_dwordx4 v[92:95], v[92:93], off offset:1024
	v_cmp_lt_i32_e32 vcc, -1, v87
	v_add_u32_e32 v87, 8, v87
	v_and_b32_e32 v186, 0xffff0000, v145
	s_waitcnt vmcnt(6)
	v_cndmask_b32_e32 v146, 0, v218, vcc
	v_cndmask_b32_e32 v152, 0, v223, vcc
	v_cndmask_b32_e32 v144, 0, v222, vcc
	v_cndmask_b32_e32 v99, 0, v221, vcc
	v_cndmask_b32_e32 v100, 0, v220, vcc
	v_cndmask_b32_e32 v101, 0, v219, vcc
	v_cndmask_b32_e32 v151, 0, v225, vcc
	v_cndmask_b32_e32 v153, 0, v224, vcc
	v_add_u32_e32 v218, 4, v86
	v_max_i32_e32 v218, 0, v218
	v_min_u32_e32 v218, 0xffff, v218
	v_mul_u32_u24_e32 v208, 0xe00, v218
	v_lshl_add_u64 v[222:223], v[56:57], 0, v[208:209]
	global_load_dwordx4 v[218:221], v[222:223], off offset:512
	s_nop 0
	global_load_dwordx4 v[222:225], v[222:223], off offset:1024
	v_lshlrev_b32_e32 v150, 16, v101
	v_and_b32_e32 v154, 0xffff0000, v101
	v_lshlrev_b32_e32 v158, 16, v100
	v_and_b32_e32 v162, 0xffff0000, v100
	v_lshlrev_b32_e32 v166, 16, v99
	v_and_b32_e32 v170, 0xffff0000, v99
	v_lshlrev_b32_e32 v140, 16, v144
	v_lshlrev_b32_e32 v142, 16, v146
	v_and_b32_e32 v144, 0xffff0000, v144
	v_and_b32_e32 v146, 0xffff0000, v146
	v_lshlrev_b32_e32 v148, 16, v152
	v_and_b32_e32 v152, 0xffff0000, v152
	v_lshlrev_b32_e32 v156, 16, v153
	v_and_b32_e32 v160, 0xffff0000, v153
	v_lshlrev_b32_e32 v164, 16, v151
	v_and_b32_e32 v168, 0xffff0000, v151
	s_waitcnt vmcnt(6)
	v_cndmask_b32_e32 v161, 0, v226, vcc
	v_cndmask_b32_e32 v167, 0, v231, vcc
	v_cndmask_b32_e32 v169, 0, v230, vcc
	v_cndmask_b32_e32 v155, 0, v229, vcc
	v_cndmask_b32_e32 v157, 0, v228, vcc
	v_cndmask_b32_e32 v159, 0, v227, vcc
	v_cndmask_b32_e32 v163, 0, v233, vcc
	v_cndmask_b32_e32 v165, 0, v232, vcc
	v_add_u32_e32 v226, 5, v86
	v_max_i32_e32 v226, 0, v226
	v_min_u32_e32 v226, 0xffff, v226
	v_mul_u32_u24_e32 v208, 0xe00, v226
	v_lshl_add_u64 v[230:231], v[56:57], 0, v[208:209]
	global_load_dwordx4 v[226:229], v[230:231], off offset:512
	s_nop 0
	global_load_dwordx4 v[230:233], v[230:231], off offset:1024
	v_and_b32_e32 v187, 0xffff0000, v163
	s_waitcnt vmcnt(6)
	v_cndmask_b32_e32 v190, 0, v234, vcc
	v_cndmask_b32_e32 v193, 0, v239, vcc
	v_cndmask_b32_e32 v194, 0, v238, vcc
	v_cndmask_b32_e32 v171, 0, v237, vcc
	v_cndmask_b32_e32 v188, 0, v236, vcc
	v_cndmask_b32_e32 v189, 0, v235, vcc
	v_cndmask_b32_e32 v191, 0, v241, vcc
	v_cndmask_b32_e32 v192, 0, v240, vcc
	v_add_u32_e32 v234, 6, v86
	v_max_i32_e32 v234, 0, v234
	v_min_u32_e32 v234, 0xffff, v234
	v_mul_u32_u24_e32 v208, 0xe00, v234
	v_lshl_add_u64 v[238:239], v[56:57], 0, v[208:209]
	global_load_dwordx4 v[234:237], v[238:239], off offset:512
	s_nop 0
	global_load_dwordx4 v[238:241], v[238:239], off offset:1024
	v_lshlrev_b32_e32 v151, 16, v189
	v_and_b32_e32 v153, 0xffff0000, v193
	s_waitcnt vmcnt(6)
	v_cndmask_b32_e32 v198, 0, v88, vcc
	v_cndmask_b32_e32 v201, 0, v93, vcc
	v_cndmask_b32_e32 v202, 0, v92, vcc
	v_cndmask_b32_e32 v195, 0, v91, vcc
	v_cndmask_b32_e32 v196, 0, v90, vcc
	v_cndmask_b32_e32 v197, 0, v89, vcc
	v_cndmask_b32_e32 v199, 0, v95, vcc
	v_cndmask_b32_e32 v200, 0, v94, vcc
	v_add_u32_e32 v88, 7, v86
	v_max_i32_e32 v88, 0, v88
	v_min_u32_e32 v88, 0xffff, v88
	v_mul_u32_u24_e32 v208, 0xe00, v88
	v_lshl_add_u64 v[92:93], v[56:57], 0, v[208:209]
	global_load_dwordx4 v[88:91], v[92:93], off offset:512
	s_nop 0
	global_load_dwordx4 v[92:95], v[92:93], off offset:1024
	s_waitcnt vmcnt(6)
	v_cndmask_b32_e32 v206, 0, v218, vcc
	v_cndmask_b32_e32 v215, 0, v223, vcc
	v_cndmask_b32_e32 v216, 0, v222, vcc
	v_cndmask_b32_e32 v203, 0, v221, vcc
	v_cndmask_b32_e32 v204, 0, v220, vcc
	v_cndmask_b32_e32 v205, 0, v219, vcc
	v_cndmask_b32_e32 v207, 0, v225, vcc
	v_cndmask_b32_e32 v214, 0, v224, vcc
	v_add_u32_e32 v218, 8, v86
	v_max_i32_e32 v218, 0, v218
	v_min_u32_e32 v218, 0xffff, v218
	v_mul_u32_u24_e32 v208, 0xe00, v218
	v_lshl_add_u64 v[222:223], v[56:57], 0, v[208:209]
	global_load_dwordx4 v[218:221], v[222:223], off offset:512
	s_nop 0
	global_load_dwordx4 v[222:225], v[222:223], off offset:1024
	s_waitcnt vmcnt(6)
	v_cndmask_b32_e32 v136, 0, v226, vcc
	v_cndmask_b32_e32 v137, 0, v231, vcc
	v_cndmask_b32_e32 v139, 0, v230, vcc
	v_cndmask_b32_e32 v124, 0, v229, vcc
	v_cndmask_b32_e32 v126, 0, v228, vcc
	v_cndmask_b32_e32 v132, 0, v227, vcc
	v_cndmask_b32_e32 v127, 0, v233, vcc
	v_cndmask_b32_e32 v133, 0, v232, vcc
	s_waitcnt vmcnt(4)
	v_cndmask_b32_e32 v138, 0, v234, vcc
	v_cndmask_b32_e32 v130, 0, v239, vcc
	v_cndmask_b32_e32 v134, 0, v238, vcc
	v_cndmask_b32_e32 v129, 0, v237, vcc
	v_cndmask_b32_e32 v131, 0, v236, vcc
	v_cndmask_b32_e32 v135, 0, v235, vcc
	v_cndmask_b32_e32 v125, 0, v241, vcc
	v_cndmask_b32_e32 v128, 0, v240, vcc
	s_waitcnt vmcnt(2)
	v_cndmask_b32_e32 v108, 0, v91, vcc
	v_cndmask_b32_e32 v110, 0, v90, vcc
	v_cndmask_b32_e32 v115, 0, v89, vcc
	v_cndmask_b32_e32 v120, 0, v88, vcc
	v_cndmask_b32_e32 v111, 0, v95, vcc
	v_cndmask_b32_e32 v116, 0, v94, vcc
	v_cndmask_b32_e32 v121, 0, v93, vcc
	v_cndmask_b32_e32 v123, 0, v92, vcc
	v_cmp_gt_u32_e32 vcc, s15, v87
	v_lshlrev_b32_e32 v208, 16, v52
	v_and_b32_e32 v52, 0xffff0000, v52
	s_waitcnt vmcnt(0)
	v_cndmask_b32_e32 v113, 0, v221, vcc
	v_cndmask_b32_e32 v117, 0, v220, vcc
	v_cndmask_b32_e32 v119, 0, v219, vcc
	v_cndmask_b32_e32 v122, 0, v218, vcc
	v_lshlrev_b32_e32 v86, 16, v97
	v_lshlrev_b32_e32 v87, 16, v161
	v_lshlrev_b32_e32 v88, 16, v98
	v_lshlrev_b32_e32 v89, 16, v169
	v_pk_mul_f32 v[100:101], v[86:87], v[88:89]
	v_and_b32_e32 v87, 0xffff0000, v161
	v_and_b32_e32 v86, 0xffff0000, v97
	v_and_b32_e32 v89, 0xffff0000, v169
	v_and_b32_e32 v88, 0xffff0000, v98
	v_pk_mul_f32 v[98:99], v[86:87], v[88:89]
	v_lshlrev_b32_e32 v86, 16, v96
	v_lshlrev_b32_e32 v87, 16, v159
	v_lshlrev_b32_e32 v88, 16, v149
	v_lshlrev_b32_e32 v89, 16, v167
	v_pk_mul_f32 v[94:95], v[86:87], v[88:89]
	v_and_b32_e32 v87, 0xffff0000, v159
	v_and_b32_e32 v86, 0xffff0000, v96
	v_and_b32_e32 v89, 0xffff0000, v167
	v_and_b32_e32 v88, 0xffff0000, v149
	v_pk_mul_f32 v[96:97], v[86:87], v[88:89]
	v_lshlrev_b32_e32 v86, 16, v143
	v_lshlrev_b32_e32 v87, 16, v157
	v_lshlrev_b32_e32 v88, 16, v147
	v_lshlrev_b32_e32 v89, 16, v165
	v_cndmask_b32_e32 v114, 0, v223, vcc
	v_cndmask_b32_e32 v118, 0, v222, vcc
	v_pk_mul_f32 v[90:91], v[86:87], v[88:89]
	v_and_b32_e32 v87, 0xffff0000, v157
	v_and_b32_e32 v86, 0xffff0000, v143
	v_and_b32_e32 v89, 0xffff0000, v165
	v_and_b32_e32 v88, 0xffff0000, v147
	v_cndmask_b32_e32 v109, 0, v225, vcc
	v_cndmask_b32_e32 v112, 0, v224, vcc
	v_pk_mul_f32 v[92:93], v[86:87], v[88:89]
	v_lshlrev_b32_e32 v86, 16, v141
	v_lshlrev_b32_e32 v87, 16, v155
	v_lshlrev_b32_e32 v88, 16, v145
	v_lshlrev_b32_e32 v89, 16, v163
	v_pk_mul_f32 v[86:87], v[86:87], v[88:89]
	v_and_b32_e32 v88, 0xffff0000, v141
	v_lshlrev_b32_e32 v143, 16, v190
	v_lshlrev_b32_e32 v141, 16, v194
	v_pk_mul_f32 v[172:173], v[60:61], v[100:101]
	v_pk_mul_f32 v[140:141], v[140:141], v[142:143]
	v_and_b32_e32 v147, 0xffff0000, v190
	v_fma_f32 v142, v8, v140, v172
	v_add_f32_e32 v142, v142, v173
	v_mul_f32_e32 v172, v142, v208
	v_pk_mul_f32 v[142:143], v[60:61], v[140:141]
	v_and_b32_e32 v145, 0xffff0000, v194
	v_fma_f32 v140, v8, v101, v142
	v_pk_mul_f32 v[174:175], v[4:5], v[98:99]
	v_add_f32_e32 v140, v140, v143
	v_pk_mul_f32 v[142:143], v[144:145], v[146:147]
	v_and_b32_e32 v89, 0xffff0000, v155
	v_fma_f32 v144, v9, v142, v174
	v_add_f32_e32 v144, v144, v175
	v_mul_f32_e32 v173, v144, v52
	v_pk_mul_f32 v[144:145], v[4:5], v[142:143]
	v_and_b32_e32 v155, 0xffff0000, v189
	v_lshlrev_b32_e32 v149, 16, v193
	v_fma_f32 v52, v9, v99, v144
	v_pk_mul_f32 v[176:177], v[66:67], v[94:95]
	v_pk_mul_f32 v[178:179], v[6:7], v[96:97]
	v_lshlrev_b32_e32 v159, 16, v188
	v_and_b32_e32 v163, 0xffff0000, v188
	v_lshlrev_b32_e32 v188, 16, v48
	v_and_b32_e32 v48, 0xffff0000, v48
	v_add_f32_e32 v52, v52, v145
	v_pk_mul_f32 v[144:145], v[148:149], v[150:151]
	v_pk_mul_f32 v[148:149], v[152:153], v[154:155]
	v_mul_f32_e32 v142, v52, v48
	v_and_b32_e32 v151, 0xffff0000, v53
	v_lshlrev_b32_e32 v150, 16, v53
	v_mov_b32_e32 v52, v144
	v_mov_b32_e32 v53, v148
	v_mov_b32_e32 v152, v176
	v_mov_b32_e32 v153, v178
	v_pk_fma_f32 v[52:53], v[10:11], v[52:53], v[152:153]
	v_mov_b32_e32 v178, v177
	v_pk_add_f32 v[52:53], v[52:53], v[178:179]
	v_mul_f32_e32 v174, v173, v173
	v_pk_mul_f32 v[52:53], v[52:53], v[150:151]
	v_fmac_f32_e32 v174, v172, v172
	v_pk_mul_f32 v[150:151], v[52:53], v[52:53]
	v_pk_mul_f32 v[146:147], v[66:67], v[144:145]
	v_add_f32_e32 v48, v150, v174
	v_add_f32_e32 v144, v151, v48
	v_pk_mul_f32 v[150:151], v[6:7], v[148:149]
	v_and_b32_e32 v153, 0xffff0000, v49
	v_lshlrev_b32_e32 v152, 16, v49
	v_mov_b32_e32 v48, v95
	v_mov_b32_e32 v49, v97
	v_mov_b32_e32 v154, v146
	v_mov_b32_e32 v155, v150
	v_pk_fma_f32 v[48:49], v[10:11], v[48:49], v[154:155]
	v_mov_b32_e32 v150, v147
	v_lshlrev_b32_e32 v157, 16, v192
	v_and_b32_e32 v161, 0xffff0000, v192
	v_pk_add_f32 v[48:49], v[48:49], v[150:151]
	v_pk_mul_f32 v[180:181], v[72:73], v[90:91]
	v_pk_mul_f32 v[182:183], v[16:17], v[92:93]
	v_pk_mul_f32 v[146:147], v[48:49], v[152:153]
	v_pk_mul_f32 v[150:151], v[156:157], v[158:159]
	v_pk_mul_f32 v[152:153], v[160:161], v[162:163]
	v_mov_b32_e32 v156, v150
	v_mov_b32_e32 v157, v152
	v_mov_b32_e32 v158, v180
	v_mov_b32_e32 v159, v182
	v_pk_fma_f32 v[156:157], v[20:21], v[156:157], v[158:159]
	v_mov_b32_e32 v182, v181
	v_and_b32_e32 v155, 0xffff0000, v54
	v_lshlrev_b32_e32 v154, 16, v54
	v_pk_add_f32 v[156:157], v[156:157], v[182:183]
	v_mul_f32_e32 v140, v140, v188
	v_mul_f32_e32 v175, v142, v142
	v_pk_mul_f32 v[154:155], v[156:157], v[154:155]
	v_fmac_f32_e32 v175, v140, v140
	v_pk_mul_f32 v[48:49], v[146:147], v[146:147]
	v_pk_mul_f32 v[156:157], v[154:155], v[154:155]
	v_add_f32_e32 v48, v48, v175
	v_add_f32_e32 v54, v156, v144
	v_add_f32_e32 v148, v49, v48
	v_pk_mul_f32 v[48:49], v[72:73], v[150:151]
	v_add_f32_e32 v144, v157, v54
	v_pk_mul_f32 v[156:157], v[16:17], v[152:153]
	v_mov_b32_e32 v160, v91
	v_mov_b32_e32 v161, v93
	v_mov_b32_e32 v162, v48
	v_mov_b32_e32 v163, v156
	v_pk_fma_f32 v[160:161], v[20:21], v[160:161], v[162:163]
	v_mov_b32_e32 v156, v49
	v_and_b32_e32 v159, 0xffff0000, v50
	v_lshlrev_b32_e32 v158, 16, v50
	v_pk_add_f32 v[48:49], v[160:161], v[156:157]
	v_pk_mul_f32 v[88:89], v[88:89], v[186:187]
	v_pk_mul_f32 v[156:157], v[48:49], v[158:159]
	v_lshlrev_b32_e32 v167, 16, v171
	v_pk_mul_f32 v[48:49], v[156:157], v[156:157]
	v_and_b32_e32 v171, 0xffff0000, v171
	v_lshlrev_b32_e32 v165, 16, v191
	v_and_b32_e32 v169, 0xffff0000, v191
	v_add_f32_e32 v48, v48, v148
	v_pk_mul_f32 v[184:185], v[78:79], v[86:87]
	v_pk_mul_f32 v[186:187], v[18:19], v[88:89]
	v_add_f32_e32 v148, v49, v48
	v_pk_mul_f32 v[158:159], v[164:165], v[166:167]
	v_pk_mul_f32 v[48:49], v[168:169], v[170:171]
	v_and_b32_e32 v163, 0xffff0000, v55
	v_lshlrev_b32_e32 v162, 16, v55
	v_mov_b32_e32 v54, v158
	v_mov_b32_e32 v55, v48
	v_mov_b32_e32 v164, v184
	v_mov_b32_e32 v165, v186
	v_pk_fma_f32 v[54:55], v[22:23], v[54:55], v[164:165]
	v_mov_b32_e32 v186, v185
	v_pk_add_f32 v[54:55], v[54:55], v[186:187]
	v_pk_mul_f32 v[160:161], v[78:79], v[158:159]
	v_pk_mul_f32 v[54:55], v[54:55], v[162:163]
	v_lshlrev_b32_e32 v164, 16, v200
	v_pk_mul_f32 v[162:163], v[54:55], v[54:55]
	v_lshlrev_b32_e32 v166, 16, v196
	v_add_f32_e32 v50, v162, v144
	v_add_f32_e32 v50, v163, v50
	v_and_b32_e32 v162, 0xffff0000, v197
	v_and_b32_e32 v163, 0xffff0000, v205
	v_lshlrev_b32_e32 v167, 16, v204
	v_lshlrev_b32_e32 v165, 16, v214
	s_waitcnt lgkmcnt(0)
	s_nop 1
	v_add_f32_dpp v50, v50, v50 quad_perm:[1,0,3,2] row_mask:0xf bank_mask:0xf
	v_and_b32_e32 v168, 0xffff0000, v200
	v_and_b32_e32 v170, 0xffff0000, v196
	v_and_b32_e32 v171, 0xffff0000, v204
	v_and_b32_e32 v169, 0xffff0000, v214
	s_waitcnt lgkmcnt(0)
	s_nop 1
	v_add_f32_dpp v50, v50, v50 quad_perm:[2,3,0,1] row_mask:0xf bank_mask:0xf
	v_lshlrev_b32_e32 v174, 16, v195
	v_lshlrev_b32_e32 v175, 16, v203
	v_and_b32_e32 v176, 0xffff0000, v199
	v_and_b32_e32 v178, 0xffff0000, v195
	s_waitcnt lgkmcnt(0)
	s_nop 1
	v_add_f32_dpp v50, v50, v50 row_half_mirror row_mask:0xf bank_mask:0xf
	v_and_b32_e32 v179, 0xffff0000, v203
	v_and_b32_e32 v177, 0xffff0000, v207
	s_waitcnt lgkmcnt(0)
	s_nop 1
	v_add_f32_dpp v50, v50, v50 row_mirror row_mask:0xf bank_mask:0xf
	s_nop 1
	v_mov_b32_e32 v144, v50
	s_nop 1
	v_permlane16_swap_b32_e32 v144, v50
	s_waitcnt lgkmcnt(0)
	v_add_f32_e32 v50, v50, v144
	v_fmamk_f32 v50, v50, 0x3b800000, v244
	v_cmp_gt_f32_e32 vcc, s7, v50
	v_mul_f32_e32 v144, 0x4b800000, v50
	s_nop 0
	v_cndmask_b32_e32 v50, v50, v144, vcc
	v_rsq_f32_e32 v50, v50
	s_nop 0
	v_mul_f32_e32 v144, 0x45800000, v50
	v_cndmask_b32_e32 v50, v50, v144, vcc
	v_mul_f32_e32 v53, v53, v50
	v_mul_f32_e32 v144, v172, v50
	v_mul_f32_e32 v150, v173, v50
	v_mul_f32_e32 v152, v52, v50
	v_cvt_pk_bf16_f32 v52, v144, v150
	v_cvt_pk_bf16_f32 v53, v152, v53
	v_mul_f32_e32 v154, v154, v50
	v_mul_f32_e32 v155, v155, v50
	v_mul_f32_e32 v158, v54, v50
	v_mul_f32_e32 v50, v55, v50
	v_cvt_pk_bf16_f32 v54, v154, v155
	v_cvt_pk_bf16_f32 v55, v158, v50
	global_store_dwordx4 v[84:85], v[52:55], off sc1
	v_mov_b32_e32 v50, v87
	v_mov_b32_e32 v154, v160
	v_pk_mul_f32 v[52:53], v[18:19], v[48:49]
	v_and_b32_e32 v55, 0xffff0000, v51
	v_lshlrev_b32_e32 v54, 16, v51
	v_mov_b32_e32 v51, v89
	v_mov_b32_e32 v155, v52
	v_pk_fma_f32 v[50:51], v[22:23], v[50:51], v[154:155]
	v_mov_b32_e32 v52, v161
	v_pk_add_f32 v[50:51], v[50:51], v[52:53]
	v_lshlrev_b32_e32 v154, 16, v201
	v_pk_mul_f32 v[50:51], v[50:51], v[54:55]
	v_lshlrev_b32_e32 v155, 16, v215
	v_pk_mul_f32 v[52:53], v[50:51], v[50:51]
	v_and_b32_e32 v160, 0xffff0000, v201
	v_add_f32_e32 v48, v52, v148
	v_add_f32_e32 v48, v53, v48
	v_and_b32_e32 v161, 0xffff0000, v215
	v_mov_b32_e32 v148, v145
	v_mov_b32_e32 v152, v151
	v_lshlrev_b32_e32 v172, 16, v199
	s_waitcnt lgkmcnt(0)
	s_nop 1
	v_add_f32_dpp v48, v48, v48 quad_perm:[1,0,3,2] row_mask:0xf bank_mask:0xf
	v_lshlrev_b32_e32 v173, 16, v207
	s_waitcnt lgkmcnt(0)
	s_nop 1
	v_add_f32_dpp v48, v48, v48 quad_perm:[2,3,0,1] row_mask:0xf bank_mask:0xf
	s_waitcnt lgkmcnt(0)
	s_nop 1
	v_add_f32_dpp v48, v48, v48 row_half_mirror row_mask:0xf bank_mask:0xf
	s_waitcnt lgkmcnt(0)
	s_nop 1
	v_add_f32_dpp v48, v48, v48 row_mirror row_mask:0xf bank_mask:0xf
	s_nop 1
	v_mov_b32_e32 v52, v48
	s_nop 1
	v_permlane16_swap_b32_e32 v52, v48
	s_waitcnt lgkmcnt(0)
	v_add_f32_e32 v48, v48, v52
	v_fmamk_f32 v48, v48, 0x3b800000, v244
	v_cmp_gt_f32_e32 vcc, s7, v48
	v_mul_f32_e32 v52, 0x4b800000, v48
	s_nop 0
	v_cndmask_b32_e32 v48, v48, v52, vcc
	v_rsq_f32_e32 v48, v48
	s_nop 0
	v_mul_f32_e32 v52, 0x45800000, v48
	v_cndmask_b32_e32 v48, v48, v52, vcc
	v_mul_f32_e32 v52, v140, v48
	v_mul_f32_e32 v53, v142, v48
	v_mul_f32_e32 v54, v146, v48
	v_mul_f32_e32 v55, v147, v48
	v_mul_f32_e32 v140, v156, v48
	v_mul_f32_e32 v142, v157, v48
	v_mul_f32_e32 v144, v50, v48
	v_mul_f32_e32 v48, v51, v48
	v_cvt_pk_bf16_f32 v50, v52, v53
	v_cvt_pk_bf16_f32 v51, v54, v55
	v_cvt_pk_bf16_f32 v52, v140, v142
	v_cvt_pk_bf16_f32 v53, v144, v48
	global_store_dwordx4 v[84:85], v[50:53], off offset:2048 sc1
	v_lshlrev_b32_e32 v48, 16, v44
	v_and_b32_e32 v54, 0xffff0000, v202
	v_lshlrev_b32_e32 v50, 16, v202
	v_lshlrev_b32_e32 v52, 16, v198
	v_lshlrev_b32_e32 v53, 16, v206
	v_lshlrev_b32_e32 v51, 16, v216
	v_pk_mul_f32 v[180:181], v[50:51], v[52:53]
	v_and_b32_e32 v146, 0xffff0000, v198
	v_pk_mov_b32 v[50:51], v[100:101], v[180:181] op_sel:[1,0]
	v_and_b32_e32 v147, 0xffff0000, v206
	v_pk_mul_f32 v[50:51], v[60:61], v[50:51]
	v_and_b32_e32 v55, 0xffff0000, v216
	v_fma_f32 v50, v8, v141, v50
	v_add_f32_e32 v50, v50, v51
	v_mul_f32_e32 v144, v50, v48
	v_pk_mul_f32 v[50:51], v[62:63], v[180:181]
	v_pk_mul_f32 v[54:55], v[54:55], v[146:147]
	v_fma_f32 v48, v0, v141, v50
	v_add_f32_e32 v48, v48, v51
	v_pk_mov_b32 v[50:51], v[98:99], v[54:55] op_sel:[1,0]
	v_lshlrev_b32_e32 v140, 16, v40
	v_pk_mul_f32 v[50:51], v[4:5], v[50:51]
	v_mul_f32_e32 v150, v48, v140
	v_fma_f32 v48, v9, v143, v50
	v_lshlrev_b32_e32 v156, 16, v197
	v_and_b32_e32 v44, 0xffff0000, v44
	v_lshlrev_b32_e32 v157, 16, v205
	v_add_f32_e32 v48, v48, v51
	v_pk_mul_f32 v[50:51], v[64:65], v[54:55]
	v_mul_f32_e32 v146, v48, v44
	v_fma_f32 v44, v1, v143, v50
	v_pk_mul_f32 v[98:99], v[154:155], v[156:157]
	v_add_f32_e32 v44, v44, v51
	v_pk_mov_b32 v[50:51], v[94:95], v[98:99] op_sel:[1,0]
	v_pk_mul_f32 v[94:95], v[160:161], v[162:163]
	v_and_b32_e32 v40, 0xffff0000, v40
	v_pk_mov_b32 v[96:97], v[96:97], v[94:95] op_sel:[1,0]
	v_pk_mul_f32 v[50:51], v[66:67], v[50:51]
	v_pk_mul_f32 v[96:97], v[6:7], v[96:97]
	v_mul_f32_e32 v147, v44, v40
	v_and_b32_e32 v101, 0xffff0000, v45
	v_lshlrev_b32_e32 v100, 16, v45
	v_mov_b32_e32 v44, v50
	v_mov_b32_e32 v45, v96
	v_pk_fma_f32 v[44:45], v[10:11], v[148:149], v[44:45]
	v_mov_b32_e32 v96, v51
	v_pk_add_f32 v[44:45], v[44:45], v[96:97]
	v_mul_f32_e32 v48, v146, v146
	v_pk_mul_f32 v[44:45], v[44:45], v[100:101]
	v_fmac_f32_e32 v48, v144, v144
	v_pk_mul_f32 v[50:51], v[44:45], v[44:45]
	v_pk_mul_f32 v[52:53], v[68:69], v[98:99]
	v_add_f32_e32 v40, v50, v48
	v_add_f32_e32 v48, v51, v40
	v_pk_mul_f32 v[50:51], v[70:71], v[94:95]
	v_and_b32_e32 v97, 0xffff0000, v41
	v_lshlrev_b32_e32 v96, 16, v41
	v_mov_b32_e32 v40, v52
	v_mov_b32_e32 v41, v50
	v_pk_fma_f32 v[40:41], v[2:3], v[148:149], v[40:41]
	v_mov_b32_e32 v50, v53
	v_pk_add_f32 v[40:41], v[40:41], v[50:51]
	v_mul_f32_e32 v140, v147, v147
	v_pk_mul_f32 v[96:97], v[40:41], v[96:97]
	v_fmac_f32_e32 v140, v150, v150
	v_pk_mul_f32 v[40:41], v[96:97], v[96:97]
	v_pk_mul_f32 v[100:101], v[164:165], v[166:167]
	v_add_f32_e32 v40, v40, v140
	v_add_f32_e32 v142, v41, v40
	v_pk_mov_b32 v[40:41], v[90:91], v[100:101] op_sel:[1,0]
	v_pk_mul_f32 v[90:91], v[168:169], v[170:171]
	v_pk_mul_f32 v[40:41], v[72:73], v[40:41]
	v_pk_mov_b32 v[52:53], v[92:93], v[90:91] op_sel:[1,0]
	v_mov_b32_e32 v140, v40
	v_pk_mul_f32 v[52:53], v[16:17], v[52:53]
	v_and_b32_e32 v93, 0xffff0000, v46
	v_mov_b32_e32 v141, v52
	v_pk_fma_f32 v[140:141], v[20:21], v[152:153], v[140:141]
	v_mov_b32_e32 v52, v41
	v_lshlrev_b32_e32 v92, 16, v46
	v_pk_add_f32 v[40:41], v[140:141], v[52:53]
	v_pk_mul_f32 v[50:51], v[74:75], v[100:101]
	v_pk_mul_f32 v[52:53], v[40:41], v[92:93]
	v_mov_b32_e32 v140, v50
	v_pk_mul_f32 v[40:41], v[52:53], v[52:53]
	v_and_b32_e32 v93, 0xffff0000, v42
	v_add_f32_e32 v40, v40, v48
	v_add_f32_e32 v145, v41, v40
	v_pk_mul_f32 v[40:41], v[76:77], v[90:91]
	v_lshlrev_b32_e32 v92, 16, v42
	v_mov_b32_e32 v141, v40
	v_pk_fma_f32 v[140:141], v[12:13], v[152:153], v[140:141]
	v_mov_b32_e32 v40, v51
	v_pk_add_f32 v[40:41], v[140:141], v[40:41]
	v_pk_mul_f32 v[140:141], v[172:173], v[174:175]
	v_pk_mul_f32 v[92:93], v[40:41], v[92:93]
	v_and_b32_e32 v143, 0xffff0000, v47
	v_pk_mul_f32 v[40:41], v[92:93], v[92:93]
	v_mov_b32_e32 v48, v159
	v_add_f32_e32 v40, v40, v142
	v_add_f32_e32 v148, v41, v40
	v_pk_mov_b32 v[40:41], v[86:87], v[140:141] op_sel:[1,0]
	v_lshlrev_b32_e32 v142, 16, v47
	v_pk_mul_f32 v[50:51], v[78:79], v[40:41]
	v_pk_mul_f32 v[40:41], v[176:177], v[178:179]
	v_mov_b32_e32 v46, v50
	v_pk_mov_b32 v[88:89], v[88:89], v[40:41] op_sel:[1,0]
	v_pk_mul_f32 v[86:87], v[80:81], v[140:141]
	v_pk_mul_f32 v[88:89], v[18:19], v[88:89]
	v_and_b32_e32 v149, 0xffff0000, v129
	v_mov_b32_e32 v47, v88
	v_pk_fma_f32 v[46:47], v[22:23], v[48:49], v[46:47]
	v_mov_b32_e32 v88, v51
	v_pk_add_f32 v[46:47], v[46:47], v[88:89]
	s_nop 0
	v_pk_mul_f32 v[46:47], v[46:47], v[142:143]
	v_lshlrev_b32_e32 v143, 16, v125
	v_pk_mul_f32 v[50:51], v[46:47], v[46:47]
	v_lshlrev_b32_e32 v142, 16, v127
	v_add_f32_e32 v42, v50, v145
	v_add_f32_e32 v42, v51, v42
	v_lshlrev_b32_e32 v145, 16, v129
	s_waitcnt lgkmcnt(0)
	s_nop 1
	v_add_f32_dpp v42, v42, v42 quad_perm:[1,0,3,2] row_mask:0xf bank_mask:0xf
	s_waitcnt lgkmcnt(0)
	s_nop 1
	v_add_f32_dpp v42, v42, v42 quad_perm:[2,3,0,1] row_mask:0xf bank_mask:0xf
	s_waitcnt lgkmcnt(0)
	s_nop 1
	v_add_f32_dpp v42, v42, v42 row_half_mirror row_mask:0xf bank_mask:0xf
	s_waitcnt lgkmcnt(0)
	s_nop 1
	v_add_f32_dpp v42, v42, v42 row_mirror row_mask:0xf bank_mask:0xf
	s_nop 1
	v_mov_b32_e32 v50, v42
	s_nop 1
	v_permlane16_swap_b32_e32 v50, v42
	s_waitcnt lgkmcnt(0)
	v_add_f32_e32 v42, v42, v50
	v_fmamk_f32 v42, v42, 0x3b800000, v244
	v_cmp_gt_f32_e32 vcc, s7, v42
	v_mul_f32_e32 v50, 0x4b800000, v42
	s_nop 0
	v_cndmask_b32_e32 v42, v42, v50, vcc
	v_rsq_f32_e32 v42, v42
	s_nop 0
	v_mul_f32_e32 v50, 0x45800000, v42
	v_cndmask_b32_e32 v42, v42, v50, vcc
	v_add_co_u32_e32 v88, vcc, s34, v84
	v_mul_f32_e32 v50, v144, v42
	v_mul_f32_e32 v51, v146, v42
	v_mul_f32_e32 v44, v44, v42
	v_addc_co_u32_e32 v89, vcc, 0, v85, vcc
	v_mul_f32_e32 v45, v45, v42
	v_mul_f32_e32 v52, v52, v42
	v_mul_f32_e32 v53, v53, v42
	v_mul_f32_e32 v46, v46, v42
	v_cvt_pk_bf16_f32 v50, v50, v51
	v_cvt_pk_bf16_f32 v51, v44, v45
	v_add_co_u32_e32 v44, vcc, s15, v84
	v_mul_f32_e32 v42, v47, v42
	v_cvt_pk_bf16_f32 v52, v52, v53
	v_cvt_pk_bf16_f32 v53, v46, v42
	s_nop 0
	v_addc_co_u32_e32 v45, vcc, 0, v85, vcc
	v_pk_mul_f32 v[46:47], v[82:83], v[40:41]
	global_store_dwordx4 v[44:45], v[50:53], off offset:-4096 sc1
	v_mov_b32_e32 v42, v86
	v_lshlrev_b32_e32 v144, 16, v124
	v_and_b32_e32 v51, 0xffff0000, v43
	v_lshlrev_b32_e32 v50, 16, v43
	v_mov_b32_e32 v43, v46
	v_pk_fma_f32 v[42:43], v[14:15], v[48:49], v[42:43]
	v_mov_b32_e32 v46, v87
	v_pk_add_f32 v[42:43], v[42:43], v[46:47]
	v_lshlrev_b32_e32 v86, 16, v132
	v_pk_mul_f32 v[42:43], v[42:43], v[50:51]
	v_lshlrev_b32_e32 v87, 16, v135
	v_pk_mul_f32 v[46:47], v[42:43], v[42:43]
	v_lshlrev_b32_e32 v53, 16, v130
	v_add_f32_e32 v46, v46, v148
	v_add_f32_e32 v46, v47, v46
	v_and_b32_e32 v148, 0xffff0000, v124
	v_lshlrev_b32_e32 v124, 16, v36
	v_and_b32_e32 v36, 0xffff0000, v36
	v_and_b32_e32 v146, 0xffff0000, v127
	s_waitcnt lgkmcnt(0)
	s_nop 1
	v_add_f32_dpp v46, v46, v46 quad_perm:[1,0,3,2] row_mask:0xf bank_mask:0xf
	v_and_b32_e32 v127, 0xffff0000, v131
	s_waitcnt lgkmcnt(0)
	s_nop 1
	v_add_f32_dpp v46, v46, v46 quad_perm:[2,3,0,1] row_mask:0xf bank_mask:0xf
	s_waitcnt lgkmcnt(0)
	s_nop 1
	v_add_f32_dpp v46, v46, v46 row_half_mirror row_mask:0xf bank_mask:0xf
	s_waitcnt lgkmcnt(0)
	s_nop 1
	v_add_f32_dpp v46, v46, v46 row_mirror row_mask:0xf bank_mask:0xf
	s_nop 1
	v_mov_b32_e32 v47, v46
	s_nop 1
	v_permlane16_swap_b32_e32 v47, v46
	s_waitcnt lgkmcnt(0)
	v_add_f32_e32 v46, v46, v47
	v_fmamk_f32 v46, v46, 0x3b800000, v244
	v_cmp_gt_f32_e32 vcc, s7, v46
	v_mul_f32_e32 v47, 0x4b800000, v46
	s_nop 0
	v_cndmask_b32_e32 v46, v46, v47, vcc
	v_rsq_f32_e32 v46, v46
	s_nop 0
	v_mul_f32_e32 v47, 0x45800000, v46
	v_cndmask_b32_e32 v46, v46, v47, vcc
	v_mul_f32_e32 v47, v150, v46
	v_mul_f32_e32 v48, v147, v46
	v_mul_f32_e32 v49, v96, v46
	v_mul_f32_e32 v50, v97, v46
	v_mul_f32_e32 v51, v92, v46
	v_mul_f32_e32 v52, v93, v46
	v_mul_f32_e32 v42, v42, v46
	v_mul_f32_e32 v43, v43, v46
	v_cvt_pk_bf16_f32 v46, v47, v48
	v_cvt_pk_bf16_f32 v47, v49, v50
	v_cvt_pk_bf16_f32 v48, v51, v52
	v_cvt_pk_bf16_f32 v49, v42, v43
	global_store_dwordx4 v[88:89], v[46:49], off offset:2048 sc1
	v_lshlrev_b32_e32 v42, 16, v139
	v_lshlrev_b32_e32 v43, 16, v134
	v_lshlrev_b32_e32 v46, 16, v136
	v_lshlrev_b32_e32 v47, 16, v138
	v_pk_mul_f32 v[42:43], v[42:43], v[46:47]
	v_mov_b32_e32 v46, v180
	v_mov_b32_e32 v47, v42
	v_pk_mul_f32 v[46:47], v[60:61], v[46:47]
	v_and_b32_e32 v48, 0xffff0000, v139
	v_fma_f32 v46, v8, v181, v46
	v_add_f32_e32 v46, v46, v47
	v_mul_f32_e32 v124, v46, v124
	v_pk_mul_f32 v[46:47], v[62:63], v[42:43]
	v_and_b32_e32 v50, 0xffff0000, v136
	v_fma_f32 v46, v0, v181, v46
	v_and_b32_e32 v51, 0xffff0000, v138
	v_and_b32_e32 v49, 0xffff0000, v134
	v_and_b32_e32 v147, 0xffff0000, v125
	v_lshlrev_b32_e32 v125, 16, v32
	v_add_f32_e32 v46, v46, v47
	v_mul_f32_e32 v125, v46, v125
	v_pk_mul_f32 v[46:47], v[48:49], v[50:51]
	v_mov_b32_e32 v48, v54
	v_mov_b32_e32 v49, v46
	v_pk_mul_f32 v[48:49], v[4:5], v[48:49]
	v_lshlrev_b32_e32 v52, 16, v137
	v_fma_f32 v48, v9, v55, v48
	v_add_f32_e32 v48, v48, v49
	v_and_b32_e32 v88, 0xffff0000, v137
	v_lshlrev_b32_e32 v97, 16, v128
	v_and_b32_e32 v137, 0xffff0000, v128
	v_mul_f32_e32 v128, v48, v36
	v_pk_mul_f32 v[48:49], v[64:65], v[46:47]
	v_and_b32_e32 v92, 0xffff0000, v132
	v_and_b32_e32 v93, 0xffff0000, v135
	v_and_b32_e32 v89, 0xffff0000, v130
	v_fma_f32 v36, v1, v55, v48
	v_add_f32_e32 v36, v36, v49
	v_pk_mul_f32 v[48:49], v[52:53], v[86:87]
	v_pk_mul_f32 v[54:55], v[88:89], v[92:93]
	v_mov_b32_e32 v50, v98
	v_mov_b32_e32 v51, v48
	v_mov_b32_e32 v86, v94
	v_mov_b32_e32 v87, v54
	v_and_b32_e32 v32, 0xffff0000, v32
	v_pk_mul_f32 v[50:51], v[66:67], v[50:51]
	v_pk_mul_f32 v[86:87], v[6:7], v[86:87]
	v_mul_f32_e32 v130, v36, v32
	v_and_b32_e32 v89, 0xffff0000, v37
	v_lshlrev_b32_e32 v88, 16, v37
	v_mov_b32_e32 v94, v99
	v_mov_b32_e32 v36, v50
	v_mov_b32_e32 v37, v86
	v_pk_fma_f32 v[36:37], v[10:11], v[94:95], v[36:37]
	v_mov_b32_e32 v86, v51
	v_pk_add_f32 v[36:37], v[36:37], v[86:87]
	v_mul_f32_e32 v129, v128, v128
	v_pk_mul_f32 v[36:37], v[36:37], v[88:89]
	v_fmac_f32_e32 v129, v124, v124
	v_pk_mul_f32 v[50:51], v[36:37], v[36:37]
	v_pk_mul_f32 v[52:53], v[68:69], v[48:49]
	v_add_f32_e32 v32, v50, v129
	v_add_f32_e32 v98, v51, v32
	v_pk_mul_f32 v[50:51], v[70:71], v[54:55]
	v_and_b32_e32 v87, 0xffff0000, v33
	v_lshlrev_b32_e32 v86, 16, v33
	v_mov_b32_e32 v32, v52
	v_mov_b32_e32 v33, v50
	v_pk_fma_f32 v[32:33], v[2:3], v[94:95], v[32:33]
	v_mov_b32_e32 v50, v53
	v_pk_add_f32 v[32:33], v[32:33], v[50:51]
	v_lshlrev_b32_e32 v96, 16, v133
	v_and_b32_e32 v136, 0xffff0000, v133
	v_lshlrev_b32_e32 v133, 16, v131
	v_mul_f32_e32 v131, v130, v130
	v_pk_mul_f32 v[50:51], v[32:33], v[86:87]
	v_lshlrev_b32_e32 v132, 16, v126
	v_and_b32_e32 v126, 0xffff0000, v126
	v_fmac_f32_e32 v131, v125, v125
	v_pk_mul_f32 v[32:33], v[50:51], v[50:51]
	v_pk_mul_f32 v[52:53], v[96:97], v[132:133]
	v_add_f32_e32 v32, v32, v131
	v_pk_mul_f32 v[88:89], v[136:137], v[126:127]
	v_add_f32_e32 v99, v33, v32
	v_mov_b32_e32 v32, v100
	v_mov_b32_e32 v33, v52
	v_mov_b32_e32 v92, v90
	v_mov_b32_e32 v93, v88
	v_pk_mul_f32 v[32:33], v[72:73], v[32:33]
	v_pk_mul_f32 v[92:93], v[16:17], v[92:93]
	v_mov_b32_e32 v90, v101
	v_mov_b32_e32 v96, v32
	v_mov_b32_e32 v97, v92
	v_pk_fma_f32 v[96:97], v[20:21], v[90:91], v[96:97]
	v_mov_b32_e32 v92, v33
	v_and_b32_e32 v95, 0xffff0000, v38
	v_lshlrev_b32_e32 v94, 16, v38
	v_pk_add_f32 v[32:33], v[96:97], v[92:93]
	v_pk_mul_f32 v[86:87], v[74:75], v[52:53]
	v_pk_mul_f32 v[92:93], v[32:33], v[94:95]
	v_mov_b32_e32 v96, v86
	v_pk_mul_f32 v[32:33], v[92:93], v[92:93]
	v_and_b32_e32 v95, 0xffff0000, v34
	v_add_f32_e32 v32, v32, v98
	v_add_f32_e32 v126, v33, v32
	v_pk_mul_f32 v[32:33], v[76:77], v[88:89]
	v_lshlrev_b32_e32 v94, 16, v34
	v_mov_b32_e32 v97, v32
	v_pk_fma_f32 v[90:91], v[12:13], v[90:91], v[96:97]
	v_mov_b32_e32 v32, v87
	v_pk_add_f32 v[32:33], v[90:91], v[32:33]
	v_pk_mul_f32 v[90:91], v[142:143], v[144:145]
	v_pk_mul_f32 v[86:87], v[32:33], v[94:95]
	v_mov_b32_e32 v98, v40
	v_pk_mul_f32 v[32:33], v[86:87], v[86:87]
	v_and_b32_e32 v101, 0xffff0000, v39
	v_add_f32_e32 v32, v32, v99
	v_add_f32_e32 v127, v33, v32
	v_mov_b32_e32 v32, v140
	v_mov_b32_e32 v33, v90
	v_pk_mul_f32 v[94:95], v[78:79], v[32:33]
	v_pk_mul_f32 v[32:33], v[146:147], v[148:149]
	v_lshlrev_b32_e32 v100, 16, v39
	v_mov_b32_e32 v99, v32
	v_pk_mul_f32 v[98:99], v[18:19], v[98:99]
	v_mov_b32_e32 v40, v141
	v_mov_b32_e32 v38, v94
	v_mov_b32_e32 v39, v98
	v_pk_fma_f32 v[38:39], v[22:23], v[40:41], v[38:39]
	v_mov_b32_e32 v98, v95
	v_pk_add_f32 v[38:39], v[38:39], v[98:99]
	v_pk_mul_f32 v[96:97], v[80:81], v[90:91]
	v_pk_mul_f32 v[38:39], v[38:39], v[100:101]
	v_and_b32_e32 v100, 0xffff0000, v110
	v_pk_mul_f32 v[94:95], v[38:39], v[38:39]
	v_and_b32_e32 v101, 0xffff0000, v117
	v_add_f32_e32 v34, v94, v126
	v_add_f32_e32 v34, v95, v34
	s_waitcnt lgkmcnt(0)
	s_nop 1
	v_add_f32_dpp v34, v34, v34 quad_perm:[1,0,3,2] row_mask:0xf bank_mask:0xf
	s_waitcnt lgkmcnt(0)
	s_nop 1
	v_add_f32_dpp v34, v34, v34 quad_perm:[2,3,0,1] row_mask:0xf bank_mask:0xf
	s_waitcnt lgkmcnt(0)
	s_nop 1
	v_add_f32_dpp v34, v34, v34 row_half_mirror row_mask:0xf bank_mask:0xf
	s_waitcnt lgkmcnt(0)
	s_nop 1
	v_add_f32_dpp v34, v34, v34 row_mirror row_mask:0xf bank_mask:0xf
	s_nop 1
	v_mov_b32_e32 v94, v34
	s_nop 1
	v_permlane16_swap_b32_e32 v94, v34
	s_waitcnt lgkmcnt(0)
	v_add_f32_e32 v34, v34, v94
	v_fmamk_f32 v34, v34, 0x3b800000, v244
	v_cmp_gt_f32_e32 vcc, s7, v34
	v_mul_f32_e32 v94, 0x4b800000, v34
	s_nop 0
	v_cndmask_b32_e32 v34, v34, v94, vcc
	v_rsq_f32_e32 v34, v34
	s_nop 0
	v_mul_f32_e32 v94, 0x45800000, v34
	v_cndmask_b32_e32 v34, v34, v94, vcc
	v_mul_f32_e32 v37, v37, v34
	v_mul_f32_e32 v94, v124, v34
	v_mul_f32_e32 v95, v128, v34
	v_mul_f32_e32 v98, v36, v34
	v_cvt_pk_bf16_f32 v36, v94, v95
	v_cvt_pk_bf16_f32 v37, v98, v37
	v_mul_f32_e32 v92, v92, v34
	v_mul_f32_e32 v93, v93, v34
	v_mul_f32_e32 v99, v38, v34
	v_mul_f32_e32 v34, v39, v34
	v_cvt_pk_bf16_f32 v38, v92, v93
	v_cvt_pk_bf16_f32 v39, v99, v34
	global_store_dwordx4 v[44:45], v[36:39], off sc1
	v_mov_b32_e32 v34, v96
	v_lshlrev_b32_e32 v96, 16, v110
	v_pk_mul_f32 v[36:37], v[82:83], v[32:33]
	v_and_b32_e32 v39, 0xffff0000, v35
	v_lshlrev_b32_e32 v38, 16, v35
	v_mov_b32_e32 v35, v36
	v_pk_fma_f32 v[34:35], v[14:15], v[40:41], v[34:35]
	v_mov_b32_e32 v36, v97
	v_pk_add_f32 v[34:35], v[34:35], v[36:37]
	v_lshlrev_b32_e32 v110, 16, v111
	v_pk_mul_f32 v[34:35], v[34:35], v[38:39]
	v_lshlrev_b32_e32 v94, 16, v116
	v_pk_mul_f32 v[36:37], v[34:35], v[34:35]
	v_and_b32_e32 v98, 0xffff0000, v116
	v_add_f32_e32 v36, v36, v127
	v_add_f32_e32 v36, v37, v36
	v_lshlrev_b32_e32 v116, 16, v108
	v_and_b32_e32 v124, 0xffff0000, v108
	v_lshlrev_b32_e32 v108, 16, v28
	v_and_b32_e32 v28, 0xffff0000, v28
	s_waitcnt lgkmcnt(0)
	s_nop 1
	v_add_f32_dpp v36, v36, v36 quad_perm:[1,0,3,2] row_mask:0xf bank_mask:0xf
	v_and_b32_e32 v92, 0xffff0000, v115
	v_and_b32_e32 v93, 0xffff0000, v119
	v_lshlrev_b32_e32 v95, 16, v112
	v_and_b32_e32 v99, 0xffff0000, v112
	s_waitcnt lgkmcnt(0)
	s_nop 1
	v_add_f32_dpp v36, v36, v36 quad_perm:[2,3,0,1] row_mask:0xf bank_mask:0xf
	v_lshlrev_b32_e32 v97, 16, v117
	v_lshlrev_b32_e32 v117, 16, v113
	s_waitcnt lgkmcnt(0)
	s_nop 1
	v_add_f32_dpp v36, v36, v36 row_half_mirror row_mask:0xf bank_mask:0xf
	s_waitcnt lgkmcnt(0)
	s_nop 1
	v_add_f32_dpp v36, v36, v36 row_mirror row_mask:0xf bank_mask:0xf
	s_nop 1
	v_mov_b32_e32 v37, v36
	s_nop 1
	v_permlane16_swap_b32_e32 v37, v36
	s_waitcnt lgkmcnt(0)
	v_add_f32_e32 v36, v36, v37
	v_fmamk_f32 v36, v36, 0x3b800000, v244
	v_cmp_gt_f32_e32 vcc, s7, v36
	v_mul_f32_e32 v37, 0x4b800000, v36
	s_nop 0
	v_cndmask_b32_e32 v36, v36, v37, vcc
	v_rsq_f32_e32 v36, v36
	s_nop 0
	v_mul_f32_e32 v37, 0x45800000, v36
	v_cndmask_b32_e32 v36, v36, v37, vcc
	v_mul_f32_e32 v37, v125, v36
	v_mul_f32_e32 v38, v130, v36
	v_mul_f32_e32 v39, v50, v36
	v_mul_f32_e32 v40, v51, v36
	v_mul_f32_e32 v41, v86, v36
	v_mul_f32_e32 v50, v87, v36
	v_mul_f32_e32 v51, v34, v36
	v_mul_f32_e32 v86, v35, v36
	v_cvt_pk_bf16_f32 v34, v37, v38
	v_cvt_pk_bf16_f32 v35, v39, v40
	v_cvt_pk_bf16_f32 v36, v41, v50
	v_cvt_pk_bf16_f32 v37, v51, v86
	global_store_dwordx4 v[44:45], v[34:37], off offset:2048 sc1
	v_and_b32_e32 v38, 0xffff0000, v123
	v_and_b32_e32 v40, 0xffff0000, v120
	v_lshlrev_b32_e32 v34, 16, v123
	v_lshlrev_b32_e32 v36, 16, v120
	v_lshlrev_b32_e32 v37, 16, v122
	v_lshlrev_b32_e32 v35, 16, v118
	v_pk_mul_f32 v[34:35], v[34:35], v[36:37]
	v_mov_b32_e32 v36, v42
	v_mov_b32_e32 v37, v34
	v_pk_mul_f32 v[34:35], v[62:63], v[34:35]
	v_pk_mul_f32 v[36:37], v[60:61], v[36:37]
	v_fma_f32 v34, v0, v43, v34
	v_lshlrev_b32_e32 v44, 16, v121
	v_and_b32_e32 v86, 0xffff0000, v121
	v_and_b32_e32 v120, 0xffff0000, v111
	v_and_b32_e32 v41, 0xffff0000, v122
	v_and_b32_e32 v39, 0xffff0000, v118
	v_lshlrev_b32_e32 v111, 16, v109
	v_and_b32_e32 v121, 0xffff0000, v109
	v_lshlrev_b32_e32 v109, 16, v24
	v_fma_f32 v36, v8, v43, v36
	v_add_f32_e32 v34, v34, v35
	v_add_f32_e32 v36, v36, v37
	v_mul_f32_e32 v109, v34, v109
	v_pk_mul_f32 v[34:35], v[38:39], v[40:41]
	v_mul_f32_e32 v108, v36, v108
	v_mov_b32_e32 v36, v46
	v_mov_b32_e32 v37, v34
	v_pk_mul_f32 v[36:37], v[4:5], v[36:37]
	v_pk_mul_f32 v[34:35], v[64:65], v[34:35]
	v_fma_f32 v36, v9, v47, v36
	v_add_f32_e32 v36, v36, v37
	v_lshlrev_b32_e32 v50, 16, v115
	v_lshlrev_b32_e32 v51, 16, v119
	v_lshlrev_b32_e32 v45, 16, v114
	v_and_b32_e32 v87, 0xffff0000, v114
	v_mul_f32_e32 v112, v36, v28
	v_fma_f32 v28, v1, v47, v34
	v_add_f32_e32 v28, v28, v35
	v_pk_mul_f32 v[34:35], v[44:45], v[50:51]
	v_pk_mul_f32 v[38:39], v[86:87], v[92:93]
	v_mov_b32_e32 v36, v48
	v_mov_b32_e32 v37, v34
	v_mov_b32_e32 v40, v54
	v_mov_b32_e32 v41, v38
	v_and_b32_e32 v24, 0xffff0000, v24
	v_pk_mul_f32 v[36:37], v[66:67], v[36:37]
	v_pk_mul_f32 v[40:41], v[6:7], v[40:41]
	v_and_b32_e32 v125, 0xffff0000, v113
	v_mul_f32_e32 v113, v28, v24
	v_and_b32_e32 v43, 0xffff0000, v29
	v_lshlrev_b32_e32 v42, 16, v29
	v_mov_b32_e32 v54, v49
	v_mov_b32_e32 v28, v36
	v_mov_b32_e32 v29, v40
	v_pk_fma_f32 v[28:29], v[10:11], v[54:55], v[28:29]
	v_mov_b32_e32 v40, v37
	v_pk_add_f32 v[28:29], v[28:29], v[40:41]
	v_mul_f32_e32 v46, v112, v112
	v_pk_mul_f32 v[28:29], v[28:29], v[42:43]
	v_fmac_f32_e32 v46, v108, v108
	v_pk_mul_f32 v[36:37], v[28:29], v[28:29]
	v_pk_mul_f32 v[34:35], v[68:69], v[34:35]
	v_add_f32_e32 v24, v36, v46
	v_add_f32_e32 v46, v37, v24
	v_pk_mul_f32 v[36:37], v[70:71], v[38:39]
	v_and_b32_e32 v39, 0xffff0000, v25
	v_lshlrev_b32_e32 v38, 16, v25
	v_mov_b32_e32 v24, v34
	v_mov_b32_e32 v25, v36
	v_pk_fma_f32 v[24:25], v[2:3], v[54:55], v[24:25]
	v_mov_b32_e32 v36, v35
	v_pk_add_f32 v[24:25], v[24:25], v[36:37]
	v_mul_f32_e32 v47, v113, v113
	v_pk_mul_f32 v[24:25], v[24:25], v[38:39]
	v_fmac_f32_e32 v47, v109, v109
	v_pk_mul_f32 v[34:35], v[24:25], v[24:25]
	v_pk_mul_f32 v[38:39], v[98:99], v[100:101]
	v_add_f32_e32 v34, v34, v47
	v_add_f32_e32 v47, v35, v34
	v_pk_mul_f32 v[34:35], v[94:95], v[96:97]
	v_mov_b32_e32 v36, v52
	v_mov_b32_e32 v37, v34
	v_mov_b32_e32 v40, v88
	v_mov_b32_e32 v41, v38
	v_pk_mul_f32 v[36:37], v[72:73], v[36:37]
	v_pk_mul_f32 v[40:41], v[16:17], v[40:41]
	v_mov_b32_e32 v88, v53
	v_mov_b32_e32 v44, v36
	v_mov_b32_e32 v45, v40
	v_pk_fma_f32 v[44:45], v[20:21], v[88:89], v[44:45]
	v_mov_b32_e32 v40, v37
	v_and_b32_e32 v43, 0xffff0000, v30
	v_lshlrev_b32_e32 v42, 16, v30
	v_pk_add_f32 v[36:37], v[44:45], v[40:41]
	v_pk_mul_f32 v[34:35], v[74:75], v[34:35]
	v_pk_mul_f32 v[36:37], v[36:37], v[42:43]
	v_pk_mul_f32 v[38:39], v[76:77], v[38:39]
	v_pk_mul_f32 v[40:41], v[36:37], v[36:37]
	v_mov_b32_e32 v42, v34
	v_mov_b32_e32 v43, v38
	v_add_f32_e32 v30, v40, v46
	v_pk_fma_f32 v[42:43], v[12:13], v[88:89], v[42:43]
	v_mov_b32_e32 v38, v35
	v_add_f32_e32 v48, v41, v30
	v_and_b32_e32 v41, 0xffff0000, v26
	v_lshlrev_b32_e32 v40, 16, v26
	v_pk_add_f32 v[34:35], v[42:43], v[38:39]
	v_pk_mul_f32 v[42:43], v[120:121], v[124:125]
	v_pk_mul_f32 v[34:35], v[34:35], v[40:41]
	v_mov_b32_e32 v40, v90
	v_pk_mul_f32 v[38:39], v[34:35], v[34:35]
	v_mov_b32_e32 v44, v32
	v_add_f32_e32 v26, v38, v47
	v_add_f32_e32 v49, v39, v26
	v_pk_mul_f32 v[38:39], v[110:111], v[116:117]
	v_mov_b32_e32 v45, v42
	v_mov_b32_e32 v41, v38
	v_pk_mul_f32 v[40:41], v[78:79], v[40:41]
	v_pk_mul_f32 v[44:45], v[18:19], v[44:45]
	v_and_b32_e32 v47, 0xffff0000, v31
	v_lshlrev_b32_e32 v46, 16, v31
	v_mov_b32_e32 v32, v91
	v_mov_b32_e32 v30, v40
	v_mov_b32_e32 v31, v44
	v_pk_fma_f32 v[30:31], v[22:23], v[32:33], v[30:31]
	v_mov_b32_e32 v44, v41
	v_pk_add_f32 v[30:31], v[30:31], v[44:45]
	v_pk_mul_f32 v[38:39], v[80:81], v[38:39]
	v_pk_mul_f32 v[30:31], v[30:31], v[46:47]
	s_nop 0
	v_pk_mul_f32 v[40:41], v[30:31], v[30:31]
	s_nop 0
	v_add_f32_e32 v26, v40, v48
	v_add_f32_e32 v26, v41, v26
	s_waitcnt lgkmcnt(0)
	s_nop 1
	v_add_f32_dpp v26, v26, v26 quad_perm:[1,0,3,2] row_mask:0xf bank_mask:0xf
	s_waitcnt lgkmcnt(0)
	s_nop 1
	v_add_f32_dpp v26, v26, v26 quad_perm:[2,3,0,1] row_mask:0xf bank_mask:0xf
	s_waitcnt lgkmcnt(0)
	s_nop 1
	v_add_f32_dpp v26, v26, v26 row_half_mirror row_mask:0xf bank_mask:0xf
	s_waitcnt lgkmcnt(0)
	s_nop 1
	v_add_f32_dpp v26, v26, v26 row_mirror row_mask:0xf bank_mask:0xf
	s_nop 1
	v_mov_b32_e32 v40, v26
	s_nop 1
	v_permlane16_swap_b32_e32 v40, v26
	s_waitcnt lgkmcnt(0)
	v_add_f32_e32 v26, v26, v40
	v_fmamk_f32 v26, v26, 0x3b800000, v244
	v_cmp_gt_f32_e32 vcc, s7, v26
	v_mul_f32_e32 v40, 0x4b800000, v26
	s_nop 0
	v_cndmask_b32_e32 v26, v26, v40, vcc
	v_rsq_f32_e32 v26, v26
	s_nop 0
	v_mul_f32_e32 v40, 0x45800000, v26
	v_cndmask_b32_e32 v26, v26, v40, vcc
	v_mul_f32_e32 v29, v29, v26
	v_mul_f32_e32 v36, v36, v26
	v_mul_f32_e32 v40, v108, v26
	v_mul_f32_e32 v41, v112, v26
	v_mul_f32_e32 v44, v28, v26
	v_mul_f32_e32 v37, v37, v26
	v_mul_f32_e32 v45, v30, v26
	v_cvt_pk_bf16_f32 v28, v40, v41
	v_cvt_pk_bf16_f32 v29, v44, v29
	v_cvt_pk_bf16_f32 v30, v36, v37
	v_add_co_u32_e32 v36, vcc, s35, v84
	v_mul_f32_e32 v26, v31, v26
	s_nop 0
	v_addc_co_u32_e32 v37, vcc, 0, v85, vcc
	v_cvt_pk_bf16_f32 v31, v45, v26
	global_store_dwordx4 v[36:37], v[28:31], off sc1
	v_mov_b32_e32 v26, v38
	s_nop 0
	v_pk_mul_f32 v[28:29], v[82:83], v[42:43]
	v_and_b32_e32 v31, 0xffff0000, v27
	v_lshlrev_b32_e32 v30, 16, v27
	v_mov_b32_e32 v27, v28
	v_pk_fma_f32 v[26:27], v[14:15], v[32:33], v[26:27]
	v_mov_b32_e32 v28, v39
	v_pk_add_f32 v[26:27], v[26:27], v[28:29]
	s_nop 0
	v_pk_mul_f32 v[26:27], v[26:27], v[30:31]
	s_nop 0
	v_pk_mul_f32 v[28:29], v[26:27], v[26:27]
	s_nop 0
	v_add_f32_e32 v28, v28, v49
	v_add_f32_e32 v28, v29, v28
	s_waitcnt lgkmcnt(0)
	s_nop 1
	v_add_f32_dpp v28, v28, v28 quad_perm:[1,0,3,2] row_mask:0xf bank_mask:0xf
	s_waitcnt lgkmcnt(0)
	s_nop 1
	v_add_f32_dpp v28, v28, v28 quad_perm:[2,3,0,1] row_mask:0xf bank_mask:0xf
	s_waitcnt lgkmcnt(0)
	s_nop 1
	v_add_f32_dpp v28, v28, v28 row_half_mirror row_mask:0xf bank_mask:0xf
	s_waitcnt lgkmcnt(0)
	s_nop 1
	v_add_f32_dpp v28, v28, v28 row_mirror row_mask:0xf bank_mask:0xf
	s_nop 1
	v_mov_b32_e32 v29, v28
	s_nop 1
	v_permlane16_swap_b32_e32 v29, v28
	s_waitcnt lgkmcnt(0)
	v_add_f32_e32 v28, v28, v29
	v_fmamk_f32 v28, v28, 0x3b800000, v244
	v_cmp_gt_f32_e32 vcc, s7, v28
	v_mul_f32_e32 v29, 0x4b800000, v28
	s_nop 0
	v_cndmask_b32_e32 v28, v28, v29, vcc
	v_rsq_f32_e32 v28, v28
	s_nop 0
	v_mul_f32_e32 v29, 0x45800000, v28
	v_cndmask_b32_e32 v28, v28, v29, vcc
	v_mul_f32_e32 v25, v25, v28
	v_mul_f32_e32 v27, v27, v28
	v_mul_f32_e32 v29, v109, v28
	v_mul_f32_e32 v30, v113, v28
	v_mul_f32_e32 v31, v24, v28
	v_mul_f32_e32 v32, v34, v28
	v_mul_f32_e32 v33, v35, v28
	v_mul_f32_e32 v34, v26, v28
	v_cvt_pk_bf16_f32 v24, v29, v30
	v_cvt_pk_bf16_f32 v25, v31, v25
	v_cvt_pk_bf16_f32 v26, v32, v33
	v_cvt_pk_bf16_f32 v27, v34, v27
	global_store_dwordx4 v[36:37], v[24:27], off offset:2048 sc1
	s_cbranch_scc1 .LBB0_227

.LBB0_231:
	s_add_i32 s17, s2, s0
	s_min_i32 s18, s17, 0xfff
	v_lshl_or_b32 v32, s18, 4, v92
	v_mov_b64_e32 v[64:65], s[84:85]
	v_mad_i64_i32 v[32:33], s[18:19], v32, s6, v[64:65]
	v_lshl_add_u64 v[32:33], v[32:33], 0, v[208:209]
	v_add_u32_e32 v95, s9, v92
	v_lshl_add_u64 v[34:35], v[32:33], 0, s[36:37]
	v_add_co_u32_e32 v32, vcc, 0xc000000, v32
	v_mad_i64_i32 v[64:65], s[18:19], v95, s6, v[64:65]
	s_nop 0
	v_addc_co_u32_e32 v33, vcc, 0, v33, vcc
	v_lshl_add_u64 v[88:89], v[64:65], 0, v[208:209]
	v_lshl_add_u64 v[90:91], v[88:89], 0, s[36:37]
	v_add_co_u32_e32 v88, vcc, s58, v88
	global_load_dwordx4 v[60:63], v[32:33], off offset:2048
	global_load_dwordx4 v[56:59], v[34:35], off offset:64
	global_load_dwordx4 v[52:55], v[34:35], off offset:128
	global_load_dwordx4 v[48:51], v[34:35], off offset:192
	global_load_dwordx4 v[44:47], v[34:35], off offset:256
	global_load_dwordx4 v[40:43], v[34:35], off offset:320
	global_load_dwordx4 v[36:39], v[34:35], off offset:384
	s_nop 0
	global_load_dwordx4 v[32:35], v[34:35], off offset:448
	v_addc_co_u32_e32 v89, vcc, 0, v89, vcc
	global_load_dwordx4 v[64:67], v[90:91], off offset:448
	global_load_dwordx4 v[68:71], v[90:91], off offset:384
	global_load_dwordx4 v[72:75], v[90:91], off offset:320
	global_load_dwordx4 v[76:79], v[90:91], off offset:256
	global_load_dwordx4 v[80:83], v[90:91], off offset:192
	global_load_dwordx4 v[84:87], v[90:91], off offset:128
	global_load_dwordx4 v[96:99], v[90:91], off offset:64
	global_load_dwordx4 v[100:103], v[88:89], off offset:2048
	v_ashrrev_i32_e32 v88, 31, v95
	v_lshrrev_b32_e32 v88, 19, v88
	v_add_u32_e32 v88, v95, v88
	v_ashrrev_i32_e32 v89, 13, v88
	v_mul_i32_i24_e32 v88, 0x2000, v89
	v_sub_u32_e32 v88, v95, v88
	v_lshl_or_b32 v90, v89, 7, v93
	v_ashrrev_i32_e32 v89, 31, v88
	v_ashrrev_i32_e32 v91, 31, v90
	v_lshl_add_u64 v[88:89], v[88:89], 3, s[40:41]
	s_cmpk_gt_i32 s17, 0xfff
	s_waitcnt vmcnt(0)
	v_mfma_f32_16x16x32_bf16 v[104:107], v[8:11], v[100:103], 0
	v_mfma_f32_16x16x32_bf16 v[108:111], v[16:19], v[100:103], 0
	v_mfma_f32_16x16x32_bf16 v[112:115], v[0:3], v[100:103], 0
	v_mfma_f32_16x16x32_bf16 v[100:103], v[4:7], v[100:103], 0
	v_mfma_f32_16x16x32_bf16 v[104:107], v[12:15], v[96:99], v[104:107]
	v_mfma_f32_16x16x32_bf16 v[108:111], v[20:23], v[96:99], v[108:111]
	v_mfma_f32_16x16x32_bf16 v[112:115], v[24:27], v[96:99], v[112:115]
	v_mfma_f32_16x16x32_bf16 v[96:99], v[28:31], v[96:99], v[100:103]
	s_nop 3
	v_lshlrev_b64 v[100:101], 16, v[90:91]
	v_lshl_add_u64 v[100:101], v[88:89], 0, v[100:101]
	global_store_dwordx2 v[100:101], v[104:105], off sc1
	v_add_co_u32_e32 v100, vcc, s13, v100
	s_nop 1
	v_addc_co_u32_e32 v101, vcc, 0, v101, vcc
	global_store_dwordx2 v[100:101], v[106:107], off sc1
	v_or_b32_e32 v100, 8, v90
	v_ashrrev_i32_e32 v101, 31, v100
	v_lshlrev_b64 v[100:101], 16, v[100:101]
	v_lshl_add_u64 v[100:101], v[88:89], 0, v[100:101]
	global_store_dwordx2 v[100:101], v[108:109], off sc1
	v_add_co_u32_e32 v100, vcc, s13, v100
	v_mfma_f32_16x16x32_bf16 v[104:107], v[0:3], v[84:87], 0
	s_nop 0
	v_addc_co_u32_e32 v101, vcc, 0, v101, vcc
	global_store_dwordx2 v[100:101], v[110:111], off sc1
	v_or_b32_e32 v100, 16, v90
	v_ashrrev_i32_e32 v101, 31, v100
	v_lshlrev_b64 v[100:101], 16, v[100:101]
	v_lshl_add_u64 v[100:101], v[88:89], 0, v[100:101]
	global_store_dwordx2 v[100:101], v[112:113], off sc1
	v_add_co_u32_e32 v100, vcc, s13, v100
	v_mfma_f32_16x16x32_bf16 v[104:107], v[24:27], v[80:83], v[104:107]
	s_nop 0
	v_addc_co_u32_e32 v101, vcc, 0, v101, vcc
	global_store_dwordx2 v[100:101], v[114:115], off sc1
	v_or_b32_e32 v100, 24, v90
	v_ashrrev_i32_e32 v101, 31, v100
	v_lshlrev_b64 v[100:101], 16, v[100:101]
	v_lshl_add_u64 v[100:101], v[88:89], 0, v[100:101]
	global_store_dwordx2 v[100:101], v[96:97], off sc1
	v_add_co_u32_e32 v96, vcc, s13, v100
	s_nop 1
	v_addc_co_u32_e32 v97, vcc, 0, v101, vcc
	global_store_dwordx2 v[96:97], v[98:99], off sc1
	v_mfma_f32_16x16x32_bf16 v[96:99], v[8:11], v[84:87], 0
	v_mfma_f32_16x16x32_bf16 v[100:103], v[16:19], v[84:87], 0
	v_mfma_f32_16x16x32_bf16 v[84:87], v[4:7], v[84:87], 0
	v_mfma_f32_16x16x32_bf16 v[96:99], v[12:15], v[80:83], v[96:99]
	v_mfma_f32_16x16x32_bf16 v[100:103], v[20:23], v[80:83], v[100:103]
	v_mfma_f32_16x16x32_bf16 v[80:83], v[28:31], v[80:83], v[84:87]
	s_nop 4
	v_or_b32_e32 v84, 32, v90
	v_ashrrev_i32_e32 v85, 31, v84
	v_lshlrev_b64 v[84:85], 16, v[84:85]
	v_lshl_add_u64 v[84:85], v[88:89], 0, v[84:85]
	global_store_dwordx2 v[84:85], v[96:97], off sc1
	v_add_co_u32_e32 v84, vcc, s13, v84
	s_nop 1
	v_addc_co_u32_e32 v85, vcc, 0, v85, vcc
	global_store_dwordx2 v[84:85], v[98:99], off sc1
	v_or_b32_e32 v84, 40, v90
	v_ashrrev_i32_e32 v85, 31, v84
	v_lshlrev_b64 v[84:85], 16, v[84:85]
	v_lshl_add_u64 v[84:85], v[88:89], 0, v[84:85]
	global_store_dwordx2 v[84:85], v[100:101], off sc1
	v_add_co_u32_e32 v84, vcc, s13, v84
	v_mfma_f32_16x16x32_bf16 v[96:99], v[0:3], v[76:79], 0
	s_nop 0
	v_addc_co_u32_e32 v85, vcc, 0, v85, vcc
	global_store_dwordx2 v[84:85], v[102:103], off sc1
	v_or_b32_e32 v84, 48, v90
	v_ashrrev_i32_e32 v85, 31, v84
	v_lshlrev_b64 v[84:85], 16, v[84:85]
	v_lshl_add_u64 v[84:85], v[88:89], 0, v[84:85]
	global_store_dwordx2 v[84:85], v[104:105], off sc1
	v_add_co_u32_e32 v84, vcc, s13, v84
	v_mfma_f32_16x16x32_bf16 v[96:99], v[24:27], v[72:75], v[96:99]
	s_nop 0
	v_addc_co_u32_e32 v85, vcc, 0, v85, vcc
	global_store_dwordx2 v[84:85], v[106:107], off sc1
	v_or_b32_e32 v84, 56, v90
	v_ashrrev_i32_e32 v85, 31, v84
	v_lshlrev_b64 v[84:85], 16, v[84:85]
	v_lshl_add_u64 v[84:85], v[88:89], 0, v[84:85]
	global_store_dwordx2 v[84:85], v[80:81], off sc1
	v_add_co_u32_e32 v80, vcc, s13, v84
	s_nop 1
	v_addc_co_u32_e32 v81, vcc, 0, v85, vcc
	global_store_dwordx2 v[80:81], v[82:83], off sc1
	v_mfma_f32_16x16x32_bf16 v[80:83], v[8:11], v[76:79], 0
	v_mfma_f32_16x16x32_bf16 v[84:87], v[16:19], v[76:79], 0
	v_mfma_f32_16x16x32_bf16 v[76:79], v[4:7], v[76:79], 0
	v_mfma_f32_16x16x32_bf16 v[80:83], v[12:15], v[72:75], v[80:83]
	v_mfma_f32_16x16x32_bf16 v[84:87], v[20:23], v[72:75], v[84:87]
	v_mfma_f32_16x16x32_bf16 v[72:75], v[28:31], v[72:75], v[76:79]
	s_nop 4
	v_or_b32_e32 v76, 64, v90
	v_ashrrev_i32_e32 v77, 31, v76
	v_lshlrev_b64 v[76:77], 16, v[76:77]
	v_lshl_add_u64 v[76:77], v[88:89], 0, v[76:77]
	global_store_dwordx2 v[76:77], v[80:81], off sc1
	v_add_co_u32_e32 v76, vcc, s13, v76
	s_nop 1
	v_addc_co_u32_e32 v77, vcc, 0, v77, vcc
	global_store_dwordx2 v[76:77], v[82:83], off sc1
	v_or_b32_e32 v76, 0x48, v90
	v_ashrrev_i32_e32 v77, 31, v76
	v_lshlrev_b64 v[76:77], 16, v[76:77]
	v_lshl_add_u64 v[76:77], v[88:89], 0, v[76:77]
	global_store_dwordx2 v[76:77], v[84:85], off sc1
	v_add_co_u32_e32 v76, vcc, s13, v76
	v_mfma_f32_16x16x32_bf16 v[80:83], v[0:3], v[68:71], 0
	s_nop 0
	v_addc_co_u32_e32 v77, vcc, 0, v77, vcc
	global_store_dwordx2 v[76:77], v[86:87], off sc1
	v_or_b32_e32 v76, 0x50, v90
	v_ashrrev_i32_e32 v77, 31, v76
	v_lshlrev_b64 v[76:77], 16, v[76:77]
	v_lshl_add_u64 v[76:77], v[88:89], 0, v[76:77]
	global_store_dwordx2 v[76:77], v[96:97], off sc1
	v_add_co_u32_e32 v76, vcc, s13, v76
	v_mfma_f32_16x16x32_bf16 v[80:83], v[24:27], v[64:67], v[80:83]
	s_nop 0
	v_addc_co_u32_e32 v77, vcc, 0, v77, vcc
	global_store_dwordx2 v[76:77], v[98:99], off sc1
	v_or_b32_e32 v76, 0x58, v90
	v_ashrrev_i32_e32 v77, 31, v76
	v_lshlrev_b64 v[76:77], 16, v[76:77]
	v_lshl_add_u64 v[76:77], v[88:89], 0, v[76:77]
	global_store_dwordx2 v[76:77], v[72:73], off sc1
	v_add_co_u32_e32 v72, vcc, s13, v76
	s_nop 1
	v_addc_co_u32_e32 v73, vcc, 0, v77, vcc
	global_store_dwordx2 v[72:73], v[74:75], off sc1
	v_mfma_f32_16x16x32_bf16 v[72:75], v[8:11], v[68:71], 0
	v_mfma_f32_16x16x32_bf16 v[76:79], v[16:19], v[68:71], 0
	v_mfma_f32_16x16x32_bf16 v[68:71], v[4:7], v[68:71], 0
	v_mfma_f32_16x16x32_bf16 v[72:75], v[12:15], v[64:67], v[72:75]
	v_mfma_f32_16x16x32_bf16 v[76:79], v[20:23], v[64:67], v[76:79]
	v_mfma_f32_16x16x32_bf16 v[64:67], v[28:31], v[64:67], v[68:71]
	s_nop 4
	v_or_b32_e32 v68, 0x60, v90
	v_ashrrev_i32_e32 v69, 31, v68
	v_lshlrev_b64 v[68:69], 16, v[68:69]
	v_lshl_add_u64 v[68:69], v[88:89], 0, v[68:69]
	global_store_dwordx2 v[68:69], v[72:73], off sc1
	v_add_co_u32_e32 v68, vcc, s13, v68
	s_nop 1
	v_addc_co_u32_e32 v69, vcc, 0, v69, vcc
	global_store_dwordx2 v[68:69], v[74:75], off sc1
	v_or_b32_e32 v68, 0x68, v90
	v_ashrrev_i32_e32 v69, 31, v68
	v_lshlrev_b64 v[68:69], 16, v[68:69]
	v_lshl_add_u64 v[68:69], v[88:89], 0, v[68:69]
	global_store_dwordx2 v[68:69], v[76:77], off sc1
	v_add_co_u32_e32 v68, vcc, s13, v68
	s_nop 1
	v_addc_co_u32_e32 v69, vcc, 0, v69, vcc
	global_store_dwordx2 v[68:69], v[78:79], off sc1
	v_or_b32_e32 v68, 0x70, v90
	v_ashrrev_i32_e32 v69, 31, v68
	v_lshlrev_b64 v[68:69], 16, v[68:69]
	v_lshl_add_u64 v[68:69], v[88:89], 0, v[68:69]
	global_store_dwordx2 v[68:69], v[80:81], off sc1
	v_add_co_u32_e32 v68, vcc, s13, v68
	s_nop 1
	v_addc_co_u32_e32 v69, vcc, 0, v69, vcc
	global_store_dwordx2 v[68:69], v[82:83], off sc1
	v_or_b32_e32 v68, 0x78, v90
	v_ashrrev_i32_e32 v69, 31, v68
	v_lshlrev_b64 v[68:69], 16, v[68:69]
	v_lshl_add_u64 v[68:69], v[88:89], 0, v[68:69]
	global_store_dwordx2 v[68:69], v[64:65], off sc1
	v_add_co_u32_e32 v64, vcc, 0x10000, v68
	s_nop 1
	v_addc_co_u32_e32 v65, vcc, 0, v69, vcc
	global_store_dwordx2 v[64:65], v[66:67], off sc1
	s_cbranch_scc1 .LBB0_230
	v_add_u32_e32 v64, s9, v94
	v_ashrrev_i32_e32 v65, 31, v64
	v_lshrrev_b32_e32 v65, 19, v65
	v_mfma_f32_16x16x32_bf16 v[68:71], v[8:11], v[60:63], 0
	v_add_u32_e32 v65, v64, v65
	v_ashrrev_i32_e32 v65, 13, v65
	v_mul_i32_i24_e32 v66, 0x2000, v65
	v_mfma_f32_16x16x32_bf16 v[72:75], v[16:19], v[60:63], 0
	v_sub_u32_e32 v64, v64, v66
	v_lshl_or_b32 v66, v65, 7, v93
	v_ashrrev_i32_e32 v65, 31, v64
	v_mfma_f32_16x16x32_bf16 v[76:79], v[0:3], v[60:63], 0
	v_ashrrev_i32_e32 v67, 31, v66
	v_lshl_add_u64 v[64:65], v[64:65], 3, s[40:41]
	v_mfma_f32_16x16x32_bf16 v[60:63], v[4:7], v[60:63], 0
	v_mfma_f32_16x16x32_bf16 v[68:71], v[12:15], v[56:59], v[68:71]
	v_mfma_f32_16x16x32_bf16 v[72:75], v[20:23], v[56:59], v[72:75]
	v_mfma_f32_16x16x32_bf16 v[76:79], v[24:27], v[56:59], v[76:79]
	v_mfma_f32_16x16x32_bf16 v[56:59], v[28:31], v[56:59], v[60:63]
	s_nop 3
	v_lshlrev_b64 v[60:61], 16, v[66:67]
	v_lshl_add_u64 v[60:61], v[64:65], 0, v[60:61]
	global_store_dwordx2 v[60:61], v[68:69], off sc1
	v_add_co_u32_e32 v60, vcc, s13, v60
	s_nop 1
	v_addc_co_u32_e32 v61, vcc, 0, v61, vcc
	global_store_dwordx2 v[60:61], v[70:71], off sc1
	v_or_b32_e32 v60, 8, v66
	v_ashrrev_i32_e32 v61, 31, v60
	v_lshlrev_b64 v[60:61], 16, v[60:61]
	v_lshl_add_u64 v[60:61], v[64:65], 0, v[60:61]
	global_store_dwordx2 v[60:61], v[72:73], off sc1
	v_add_co_u32_e32 v60, vcc, s13, v60
	v_mfma_f32_16x16x32_bf16 v[68:71], v[0:3], v[52:55], 0
	s_nop 0
	v_addc_co_u32_e32 v61, vcc, 0, v61, vcc
	global_store_dwordx2 v[60:61], v[74:75], off sc1
	v_or_b32_e32 v60, 16, v66
	v_ashrrev_i32_e32 v61, 31, v60
	v_lshlrev_b64 v[60:61], 16, v[60:61]
	v_lshl_add_u64 v[60:61], v[64:65], 0, v[60:61]
	global_store_dwordx2 v[60:61], v[76:77], off sc1
	v_add_co_u32_e32 v60, vcc, s13, v60
	v_mfma_f32_16x16x32_bf16 v[68:71], v[24:27], v[48:51], v[68:71]
	s_nop 0
	v_addc_co_u32_e32 v61, vcc, 0, v61, vcc
	global_store_dwordx2 v[60:61], v[78:79], off sc1
	v_or_b32_e32 v60, 24, v66
	v_ashrrev_i32_e32 v61, 31, v60
	v_lshlrev_b64 v[60:61], 16, v[60:61]
	v_lshl_add_u64 v[60:61], v[64:65], 0, v[60:61]
	global_store_dwordx2 v[60:61], v[56:57], off sc1
	v_add_co_u32_e32 v56, vcc, s13, v60
	s_nop 1
	v_addc_co_u32_e32 v57, vcc, 0, v61, vcc
	global_store_dwordx2 v[56:57], v[58:59], off sc1
	v_mfma_f32_16x16x32_bf16 v[56:59], v[8:11], v[52:55], 0
	v_mfma_f32_16x16x32_bf16 v[60:63], v[16:19], v[52:55], 0
	v_mfma_f32_16x16x32_bf16 v[52:55], v[4:7], v[52:55], 0
	v_mfma_f32_16x16x32_bf16 v[56:59], v[12:15], v[48:51], v[56:59]
	v_mfma_f32_16x16x32_bf16 v[60:63], v[20:23], v[48:51], v[60:63]
	v_mfma_f32_16x16x32_bf16 v[48:51], v[28:31], v[48:51], v[52:55]
	s_nop 4
	v_or_b32_e32 v52, 32, v66
	v_ashrrev_i32_e32 v53, 31, v52
	v_lshlrev_b64 v[52:53], 16, v[52:53]
	v_lshl_add_u64 v[52:53], v[64:65], 0, v[52:53]
	global_store_dwordx2 v[52:53], v[56:57], off sc1
	v_add_co_u32_e32 v52, vcc, s13, v52
	s_nop 1
	v_addc_co_u32_e32 v53, vcc, 0, v53, vcc
	global_store_dwordx2 v[52:53], v[58:59], off sc1
	v_or_b32_e32 v52, 40, v66
	v_ashrrev_i32_e32 v53, 31, v52
	v_lshlrev_b64 v[52:53], 16, v[52:53]
	v_lshl_add_u64 v[52:53], v[64:65], 0, v[52:53]
	global_store_dwordx2 v[52:53], v[60:61], off sc1
	v_add_co_u32_e32 v52, vcc, s13, v52
	v_mfma_f32_16x16x32_bf16 v[56:59], v[0:3], v[44:47], 0
	s_nop 0
	v_addc_co_u32_e32 v53, vcc, 0, v53, vcc
	global_store_dwordx2 v[52:53], v[62:63], off sc1
	v_or_b32_e32 v52, 48, v66
	v_ashrrev_i32_e32 v53, 31, v52
	v_lshlrev_b64 v[52:53], 16, v[52:53]
	v_lshl_add_u64 v[52:53], v[64:65], 0, v[52:53]
	global_store_dwordx2 v[52:53], v[68:69], off sc1
	v_add_co_u32_e32 v52, vcc, s13, v52
	v_mfma_f32_16x16x32_bf16 v[56:59], v[24:27], v[40:43], v[56:59]
	s_nop 0
	v_addc_co_u32_e32 v53, vcc, 0, v53, vcc
	global_store_dwordx2 v[52:53], v[70:71], off sc1
	v_or_b32_e32 v52, 56, v66
	v_ashrrev_i32_e32 v53, 31, v52
	v_lshlrev_b64 v[52:53], 16, v[52:53]
	v_lshl_add_u64 v[52:53], v[64:65], 0, v[52:53]
	global_store_dwordx2 v[52:53], v[48:49], off sc1
	v_add_co_u32_e32 v48, vcc, s13, v52
	s_nop 1
	v_addc_co_u32_e32 v49, vcc, 0, v53, vcc
	global_store_dwordx2 v[48:49], v[50:51], off sc1
	v_mfma_f32_16x16x32_bf16 v[48:51], v[8:11], v[44:47], 0
	v_mfma_f32_16x16x32_bf16 v[52:55], v[16:19], v[44:47], 0
	v_mfma_f32_16x16x32_bf16 v[44:47], v[4:7], v[44:47], 0
	v_mfma_f32_16x16x32_bf16 v[48:51], v[12:15], v[40:43], v[48:51]
	v_mfma_f32_16x16x32_bf16 v[52:55], v[20:23], v[40:43], v[52:55]
	v_mfma_f32_16x16x32_bf16 v[40:43], v[28:31], v[40:43], v[44:47]
	s_nop 4
	v_or_b32_e32 v44, 64, v66
	v_ashrrev_i32_e32 v45, 31, v44
	v_lshlrev_b64 v[44:45], 16, v[44:45]
	v_lshl_add_u64 v[44:45], v[64:65], 0, v[44:45]
	global_store_dwordx2 v[44:45], v[48:49], off sc1
	v_add_co_u32_e32 v44, vcc, s13, v44
	s_nop 1
	v_addc_co_u32_e32 v45, vcc, 0, v45, vcc
	global_store_dwordx2 v[44:45], v[50:51], off sc1
	v_or_b32_e32 v44, 0x48, v66
	v_ashrrev_i32_e32 v45, 31, v44
	v_lshlrev_b64 v[44:45], 16, v[44:45]
	v_lshl_add_u64 v[44:45], v[64:65], 0, v[44:45]
	global_store_dwordx2 v[44:45], v[52:53], off sc1
	v_add_co_u32_e32 v44, vcc, s13, v44
	v_mfma_f32_16x16x32_bf16 v[48:51], v[0:3], v[36:39], 0
	s_nop 0
	v_addc_co_u32_e32 v45, vcc, 0, v45, vcc
	global_store_dwordx2 v[44:45], v[54:55], off sc1
	v_or_b32_e32 v44, 0x50, v66
	v_ashrrev_i32_e32 v45, 31, v44
	v_lshlrev_b64 v[44:45], 16, v[44:45]
	v_lshl_add_u64 v[44:45], v[64:65], 0, v[44:45]
	global_store_dwordx2 v[44:45], v[56:57], off sc1
	v_add_co_u32_e32 v44, vcc, s13, v44
	v_mfma_f32_16x16x32_bf16 v[48:51], v[24:27], v[32:35], v[48:51]
	s_nop 0
	v_addc_co_u32_e32 v45, vcc, 0, v45, vcc
	global_store_dwordx2 v[44:45], v[58:59], off sc1
	v_or_b32_e32 v44, 0x58, v66
	v_ashrrev_i32_e32 v45, 31, v44
	v_lshlrev_b64 v[44:45], 16, v[44:45]
	v_lshl_add_u64 v[44:45], v[64:65], 0, v[44:45]
	global_store_dwordx2 v[44:45], v[40:41], off sc1
	v_add_co_u32_e32 v40, vcc, s13, v44
	s_nop 1
	v_addc_co_u32_e32 v41, vcc, 0, v45, vcc
	global_store_dwordx2 v[40:41], v[42:43], off sc1
	v_mfma_f32_16x16x32_bf16 v[40:43], v[8:11], v[36:39], 0
	v_mfma_f32_16x16x32_bf16 v[44:47], v[16:19], v[36:39], 0
	v_mfma_f32_16x16x32_bf16 v[36:39], v[4:7], v[36:39], 0
	v_mfma_f32_16x16x32_bf16 v[40:43], v[12:15], v[32:35], v[40:43]
	v_mfma_f32_16x16x32_bf16 v[44:47], v[20:23], v[32:35], v[44:47]
	v_mfma_f32_16x16x32_bf16 v[32:35], v[28:31], v[32:35], v[36:39]
	s_nop 4
	v_or_b32_e32 v36, 0x60, v66
	v_ashrrev_i32_e32 v37, 31, v36
	v_lshlrev_b64 v[36:37], 16, v[36:37]
	v_lshl_add_u64 v[36:37], v[64:65], 0, v[36:37]
	global_store_dwordx2 v[36:37], v[40:41], off sc1
	v_add_co_u32_e32 v36, vcc, s13, v36
	s_nop 1
	v_addc_co_u32_e32 v37, vcc, 0, v37, vcc
	global_store_dwordx2 v[36:37], v[42:43], off sc1
	v_or_b32_e32 v36, 0x68, v66
	v_ashrrev_i32_e32 v37, 31, v36
	v_lshlrev_b64 v[36:37], 16, v[36:37]
	v_lshl_add_u64 v[36:37], v[64:65], 0, v[36:37]
	global_store_dwordx2 v[36:37], v[44:45], off sc1
	v_add_co_u32_e32 v36, vcc, s13, v36
	s_nop 1
	v_addc_co_u32_e32 v37, vcc, 0, v37, vcc
	global_store_dwordx2 v[36:37], v[46:47], off sc1
	v_or_b32_e32 v36, 0x70, v66
	v_ashrrev_i32_e32 v37, 31, v36
	v_lshlrev_b64 v[36:37], 16, v[36:37]
	v_lshl_add_u64 v[36:37], v[64:65], 0, v[36:37]
	global_store_dwordx2 v[36:37], v[48:49], off sc1
	v_add_co_u32_e32 v36, vcc, s13, v36
	s_nop 1
	v_addc_co_u32_e32 v37, vcc, 0, v37, vcc
	global_store_dwordx2 v[36:37], v[50:51], off sc1
	v_or_b32_e32 v36, 0x78, v66
	v_ashrrev_i32_e32 v37, 31, v36
	v_lshlrev_b64 v[36:37], 16, v[36:37]
	v_lshl_add_u64 v[36:37], v[64:65], 0, v[36:37]
	global_store_dwordx2 v[36:37], v[32:33], off sc1
	v_add_co_u32_e32 v32, vcc, 0x10000, v36
	s_nop 1
	v_addc_co_u32_e32 v33, vcc, 0, v37, vcc
	global_store_dwordx2 v[32:33], v[34:35], off sc1
	s_branch .LBB0_230

.LBB0_300:
	v_lshl_add_u64 v[40:41], v[2:3], 2, s[28:29]
	global_store_dword v[40:41], v38, off sc1
	v_lshl_add_u64 v[4:5], v[4:5], 0, s[24:25]
	s_andn2_b64 vcc, exec, s[26:27]
	s_waitcnt vmcnt(4)
	v_mov_b64_e32 v[46:47], v[30:31]
	v_mov_b64_e32 v[42:43], v[6:7]
	v_mov_b64_e32 v[40:41], v[8:9]
	v_mov_b64_e32 v[38:39], v[10:11]
	v_mov_b64_e32 v[54:55], v[12:13]
	v_mov_b64_e32 v[50:51], v[14:15]
	v_mov_b64_e32 v[48:49], v[16:17]
	v_mov_b64_e32 v[44:45], v[18:19]
	v_mov_b64_e32 v[62:63], v[20:21]
	v_mov_b64_e32 v[58:59], v[22:23]
	v_mov_b64_e32 v[56:57], v[24:25]
	v_mov_b64_e32 v[52:53], v[26:27]
	v_mov_b64_e32 v[68:69], v[28:29]
	s_waitcnt vmcnt(3)
	v_mov_b64_e32 v[66:67], v[32:33]
	s_waitcnt vmcnt(2)
	v_mov_b64_e32 v[64:65], v[34:35]
	s_waitcnt vmcnt(1)
	v_mov_b64_e32 v[60:61], v[36:37]
	s_mov_b32 s28, s0
	s_cbranch_vccz .LBB0_307

.LBB0_303:
	v_pk_add_f32 v[146:147], v[46:47], v[62:63]
	v_pk_add_f32 v[46:47], v[46:47], v[62:63] neg_lo:[0,1] neg_hi:[0,1]
	v_pk_add_f32 v[62:63], v[54:55], v[68:69]
	v_pk_add_f32 v[54:55], v[54:55], v[68:69] neg_lo:[0,1] neg_hi:[0,1]
	s_mov_b32 s39, s8
	v_xor_b32_e32 v69, 0x80000000, v54
	v_mov_b32_e32 v68, v55
	v_pk_add_f32 v[148:149], v[46:47], v[68:69]
	v_pk_add_f32 v[46:47], v[46:47], v[68:69] neg_lo:[0,1] neg_hi:[0,1]
	v_pk_add_f32 v[68:69], v[42:43], v[58:59]
	v_pk_add_f32 v[42:43], v[42:43], v[58:59] neg_lo:[0,1] neg_hi:[0,1]
	v_pk_add_f32 v[58:59], v[50:51], v[66:67]
	v_pk_add_f32 v[50:51], v[50:51], v[66:67] neg_lo:[0,1] neg_hi:[0,1]
	v_pk_add_f32 v[54:55], v[146:147], v[62:63]
	v_xor_b32_e32 v67, 0x80000000, v50
	v_mov_b32_e32 v66, v51
	v_pk_add_f32 v[62:63], v[146:147], v[62:63] neg_lo:[0,1] neg_hi:[0,1]
	v_pk_add_f32 v[146:147], v[42:43], v[66:67]
	v_pk_add_f32 v[42:43], v[42:43], v[66:67] neg_lo:[0,1] neg_hi:[0,1]
	v_pk_add_f32 v[66:67], v[40:41], v[56:57]
	v_pk_add_f32 v[40:41], v[40:41], v[56:57] neg_lo:[0,1] neg_hi:[0,1]
	v_pk_add_f32 v[56:57], v[48:49], v[64:65]
	v_pk_add_f32 v[48:49], v[48:49], v[64:65] neg_lo:[0,1] neg_hi:[0,1]
	v_pk_add_f32 v[50:51], v[68:69], v[58:59]
	v_xor_b32_e32 v65, 0x80000000, v48
	v_mov_b32_e32 v64, v49
	v_pk_add_f32 v[58:59], v[68:69], v[58:59] neg_lo:[0,1] neg_hi:[0,1]
	v_pk_add_f32 v[68:69], v[40:41], v[64:65]
	v_pk_add_f32 v[40:41], v[40:41], v[64:65] neg_lo:[0,1] neg_hi:[0,1]
	v_pk_add_f32 v[64:65], v[38:39], v[52:53]
	v_pk_add_f32 v[38:39], v[38:39], v[52:53] neg_lo:[0,1] neg_hi:[0,1]
	v_pk_add_f32 v[52:53], v[44:45], v[60:61]
	v_pk_add_f32 v[44:45], v[44:45], v[60:61] neg_lo:[0,1] neg_hi:[0,1]
	v_pk_add_f32 v[48:49], v[66:67], v[56:57]
	v_xor_b32_e32 v61, 0x80000000, v44
	v_mov_b32_e32 v60, v45
	v_pk_add_f32 v[56:57], v[66:67], v[56:57] neg_lo:[0,1] neg_hi:[0,1]
	v_pk_add_f32 v[66:67], v[38:39], v[60:61]
	v_pk_add_f32 v[38:39], v[38:39], v[60:61] neg_lo:[0,1] neg_hi:[0,1]
	v_pk_mul_f32 v[60:61], v[146:147], s[8:9] op_sel_hi:[1,0]
	v_pk_add_f32 v[44:45], v[64:65], v[52:53]
	v_pk_add_f32 v[52:53], v[64:65], v[52:53] neg_lo:[0,1] neg_hi:[0,1]
	v_pk_fma_f32 v[64:65], v[146:147], s[10:11], v[60:61] op_sel:[0,0,1] op_sel_hi:[1,0,0]
	v_pk_fma_f32 v[60:61], v[146:147], s[10:11], v[60:61] op_sel:[0,0,1] op_sel_hi:[1,0,0] neg_lo:[0,0,1] neg_hi:[0,0,1]
	s_waitcnt lgkmcnt(0)
	v_mov_b32_e32 v65, v61
	v_pk_mul_f32 v[60:61], v[68:69], s[12:13] op_sel_hi:[1,0]
	s_barrier
	v_pk_fma_f32 v[146:147], v[68:69], s[12:13], v[60:61] op_sel:[0,0,1] op_sel_hi:[1,0,0]
	v_pk_fma_f32 v[60:61], v[68:69], s[12:13], v[60:61] op_sel_hi:[1,0,0] neg_lo:[0,0,1] neg_hi:[0,0,1]
	v_pk_mul_f32 v[68:69], v[66:67], s[10:11] op_sel_hi:[1,0]
	v_mov_b32_e32 v147, v61
	v_pk_fma_f32 v[150:151], v[66:67], s[8:9], v[68:69] op_sel:[0,0,1] op_sel_hi:[1,0,0]
	v_pk_fma_f32 v[66:67], v[66:67], s[8:9], v[68:69] op_sel:[0,0,1] op_sel_hi:[1,0,0] neg_lo:[0,0,1] neg_hi:[0,0,1]
	s_nop 0
	v_mov_b32_e32 v151, v67
	v_pk_mul_f32 v[66:67], v[58:59], s[12:13] op_sel_hi:[1,0]
	v_pk_add_f32 v[60:61], v[64:65], v[150:151]
	v_pk_fma_f32 v[68:69], v[58:59], s[12:13], v[66:67] op_sel:[0,0,1] op_sel_hi:[1,0,0]
	v_pk_fma_f32 v[58:59], v[58:59], s[12:13], v[66:67] op_sel_hi:[1,0,0] neg_lo:[0,0,1] neg_hi:[0,0,1]
	v_pk_fma_f32 v[66:67], v[56:57], 0, v[56:57] op_sel:[0,0,1] op_sel_hi:[1,0,0]
	v_pk_fma_f32 v[56:57], v[56:57], 0, v[56:57] op_sel:[0,0,1] op_sel_hi:[1,0,0] neg_lo:[0,0,1] neg_hi:[0,0,1]
	v_pk_add_f32 v[64:65], v[64:65], v[150:151] neg_lo:[0,1] neg_hi:[0,1]
	v_mov_b32_e32 v67, v57
	v_pk_mul_f32 v[56:57], v[52:53], s[14:15] op_sel_hi:[1,0]
	v_mov_b32_e32 v69, v59
	v_pk_fma_f32 v[152:153], v[52:53], s[14:15], v[56:57] op_sel:[0,0,1] op_sel_hi:[1,0,0] neg_lo:[0,0,1] neg_hi:[0,0,1]
	v_pk_fma_f32 v[52:53], v[52:53], s[14:15], v[56:57] op_sel_hi:[1,0,0]
	s_ashr_i32 s2, s28, 5
	v_mov_b32_e32 v153, v53
	v_pk_mul_f32 v[52:53], v[42:43], s[10:11] op_sel_hi:[1,0]
	v_pk_add_f32 v[58:59], v[68:69], v[152:153]
	v_pk_fma_f32 v[56:57], v[42:43], s[8:9], v[52:53] op_sel:[0,0,1] op_sel_hi:[1,0,0]
	v_pk_fma_f32 v[42:43], v[42:43], s[8:9], v[52:53] op_sel:[0,0,1] op_sel_hi:[1,0,0] neg_lo:[0,0,1] neg_hi:[0,0,1]
	s_mov_b32 s9, s10
	v_mov_b32_e32 v57, v43
	v_pk_mul_f32 v[42:43], v[40:41], s[14:15] op_sel_hi:[1,0]
	s_and_b32 s3, s28, 31
	v_pk_fma_f32 v[52:53], v[40:41], s[14:15], v[42:43] op_sel:[0,0,1] op_sel_hi:[1,0,0] neg_lo:[0,0,1] neg_hi:[0,0,1]
	v_pk_fma_f32 v[40:41], v[40:41], s[14:15], v[42:43] op_sel_hi:[1,0,0]
	v_pk_add_f32 v[42:43], v[54:55], v[48:49] neg_lo:[0,1] neg_hi:[0,1]
	v_mov_b32_e32 v53, v41
	v_pk_mul_f32 v[40:41], v[38:39], s[8:9] op_sel:[1,0]
	s_cmp_eq_u32 s3, 0
	v_pk_fma_f32 v[38:39], v[38:39], s[38:39], v[40:41] op_sel_hi:[0,1,1] neg_lo:[0,0,1] neg_hi:[0,0,1]
	v_pk_add_f32 v[40:41], v[54:55], v[48:49]
	v_pk_add_f32 v[48:49], v[50:51], v[44:45]
	v_pk_add_f32 v[44:45], v[50:51], v[44:45] neg_lo:[0,1] neg_hi:[0,1]
	s_nop 0
	v_xor_b32_e32 v51, 0x80000000, v44
	v_mov_b32_e32 v50, v45
	v_pk_add_f32 v[44:45], v[40:41], v[48:49]
	v_pk_add_f32 v[40:41], v[40:41], v[48:49] neg_lo:[0,1] neg_hi:[0,1]
	v_pk_add_f32 v[48:49], v[148:149], v[146:147]
	v_pk_add_f32 v[54:55], v[42:43], v[50:51]
	v_pk_add_f32 v[42:43], v[42:43], v[50:51] neg_lo:[0,1] neg_hi:[0,1]
	v_pk_add_f32 v[50:51], v[148:149], v[146:147] neg_lo:[0,1] neg_hi:[0,1]
	v_xor_b32_e32 v147, 0x80000000, v64
	v_mov_b32_e32 v146, v65
	v_pk_add_f32 v[64:65], v[48:49], v[60:61]
	v_pk_add_f32 v[48:49], v[48:49], v[60:61] neg_lo:[0,1] neg_hi:[0,1]
	v_pk_add_f32 v[60:61], v[62:63], v[66:67]
	v_pk_add_f32 v[62:63], v[62:63], v[66:67] neg_lo:[0,1] neg_hi:[0,1]
	v_pk_add_f32 v[66:67], v[68:69], v[152:153] neg_lo:[0,1] neg_hi:[0,1]
	v_pk_add_f32 v[148:149], v[50:51], v[146:147]
	v_xor_b32_e32 v69, 0x80000000, v66
	v_mov_b32_e32 v68, v67
	v_pk_add_f32 v[50:51], v[50:51], v[146:147] neg_lo:[0,1] neg_hi:[0,1]
	v_pk_add_f32 v[66:67], v[60:61], v[58:59]
	v_pk_add_f32 v[146:147], v[62:63], v[68:69]
	v_pk_add_f32 v[58:59], v[60:61], v[58:59] neg_lo:[0,1] neg_hi:[0,1]
	v_pk_add_f32 v[60:61], v[62:63], v[68:69] neg_lo:[0,1] neg_hi:[0,1]
	v_pk_add_f32 v[62:63], v[46:47], v[52:53]
	v_pk_add_f32 v[46:47], v[46:47], v[52:53] neg_lo:[0,1] neg_hi:[0,1]
	v_pk_add_f32 v[52:53], v[56:57], v[38:39]
	v_pk_add_f32 v[38:39], v[56:57], v[38:39] neg_lo:[0,1] neg_hi:[0,1]
	s_nop 0
	v_xor_b32_e32 v57, 0x80000000, v38
	v_mov_b32_e32 v56, v39
	v_pk_add_f32 v[38:39], v[62:63], v[52:53]
	v_pk_add_f32 v[68:69], v[46:47], v[56:57]
	v_pk_add_f32 v[52:53], v[62:63], v[52:53] neg_lo:[0,1] neg_hi:[0,1]
	v_pk_add_f32 v[46:47], v[46:47], v[56:57] neg_lo:[0,1] neg_hi:[0,1]
	ds_write2_b64 v142, v[44:45], v[64:65] offset1:1
	ds_write2_b64 v142, v[54:55], v[148:149] offset0:4 offset1:5
	ds_write2_b64 v142, v[40:41], v[48:49] offset0:8 offset1:9
	ds_write2_b64 v142, v[42:43], v[50:51] offset0:12 offset1:13
	ds_write2_b64 v142, v[66:67], v[38:39] offset0:2 offset1:3
	ds_write2_b64 v142, v[146:147], v[68:69] offset0:6 offset1:7
	ds_write2_b64 v142, v[58:59], v[52:53] offset0:10 offset1:11
	ds_write2_b64 v142, v[60:61], v[46:47] offset0:14 offset1:15
	s_waitcnt lgkmcnt(0)
	s_barrier
	ds_read_b64 v[38:39], v143
	ds_read_b64 v[40:41], v70
	ds_read_b64 v[42:43], v71 offset:4096
	ds_read_b64 v[44:45], v72 offset:8192
	ds_read_b64 v[46:47], v73 offset:12288
	ds_read_b64 v[48:49], v74 offset:16384
	ds_read_b64 v[50:51], v75 offset:20480
	ds_read_b64 v[52:53], v76 offset:24576
	ds_read_b64 v[54:55], v77 offset:28672
	ds_read_b64 v[56:57], v78 offset:32768
	ds_read_b64 v[58:59], v79 offset:36864
	ds_read_b64 v[60:61], v80 offset:40960
	ds_read_b64 v[62:63], v81 offset:45056
	ds_read_b64 v[64:65], v82 offset:49152
	ds_read_b64 v[66:67], v83 offset:53248
	ds_read_b64 v[68:69], v84 offset:57344
	ds_read_b64 v[146:147], v85 offset:61440
	s_waitcnt lgkmcnt(14)
	v_pk_mul_f32 v[148:149], v[38:39], v[42:43] op_sel:[1,1] op_sel_hi:[0,1]
	v_pk_fma_f32 v[150:151], v[38:39], v[42:43], v[148:149] neg_lo:[0,0,1] neg_hi:[0,0,1]
	v_pk_fma_f32 v[42:43], v[38:39], v[42:43], v[148:149] op_sel_hi:[1,0,1]
	s_waitcnt lgkmcnt(0)
	v_mov_b32_e32 v151, v43
	v_pk_mul_f32 v[42:43], v[38:39], v[38:39] op_sel:[1,1] op_sel_hi:[1,0]
	s_barrier
	v_pk_fma_f32 v[148:149], v[38:39], v[38:39], v[42:43] op_sel_hi:[1,0,1] neg_lo:[0,0,1] neg_hi:[0,0,1]
	v_pk_fma_f32 v[42:43], v[38:39], v[38:39], v[42:43] op_sel_hi:[1,0,1]
	v_mov_b32_e32 v152, v148
	v_mov_b32_e32 v153, v43
	v_pk_mul_f32 v[42:43], v[42:43], v[44:45] op_sel:[1,1] op_sel_hi:[1,0]
	s_nop 0
	v_pk_fma_f32 v[154:155], v[148:149], v[44:45], v[42:43] neg_lo:[0,0,1] neg_hi:[0,0,1]
	v_pk_fma_f32 v[42:43], v[148:149], v[44:45], v[42:43] op_sel_hi:[0,1,1]
	v_pk_mul_f32 v[44:45], v[38:39], v[152:153] op_sel:[1,0] op_sel_hi:[0,1]
	v_mov_b32_e32 v155, v43
	v_pk_mul_f32 v[42:43], v[38:39], v[152:153]
	v_pk_add_f32 v[44:45], v[44:45], v[44:45] op_sel:[0,1] op_sel_hi:[0,1]
	v_pk_mul_f32 v[148:149], v[46:47], v[44:45]
	v_pk_add_f32 v[42:43], v[42:43], v[42:43] op_sel:[0,1] op_sel_hi:[0,1] neg_lo:[0,1] neg_hi:[0,1]
	v_pk_fma_f32 v[152:153], v[46:47], v[42:43], v[148:149] op_sel:[0,0,1] op_sel_hi:[1,1,0] neg_lo:[0,0,1] neg_hi:[0,0,1]
	v_pk_fma_f32 v[46:47], v[46:47], v[42:43], v[148:149] op_sel:[0,0,1] op_sel_hi:[1,1,0]
	v_pk_mul_f32 v[44:45], v[38:39], v[44:45]
	v_mov_b32_e32 v153, v47
	v_pk_fma_f32 v[46:47], v[38:39], v[42:43], v[44:45] op_sel:[0,0,1] op_sel_hi:[1,1,0] neg_lo:[0,0,1] neg_hi:[0,0,1]
	v_pk_fma_f32 v[42:43], v[38:39], v[42:43], v[44:45] op_sel:[0,0,1] op_sel_hi:[1,1,0]
	v_mov_b32_e32 v44, v46
	v_mov_b32_e32 v45, v43
	v_pk_mul_f32 v[42:43], v[48:49], v[42:43] op_sel:[1,1] op_sel_hi:[0,1]
	v_pk_fma_f32 v[148:149], v[48:49], v[46:47], v[42:43] neg_lo:[0,0,1] neg_hi:[0,0,1]
	v_pk_fma_f32 v[42:43], v[48:49], v[46:47], v[42:43] op_sel_hi:[1,0,1]
	s_nop 0
	v_mov_b32_e32 v149, v43
	v_pk_mul_f32 v[42:43], v[38:39], v[44:45]
	v_pk_mul_f32 v[44:45], v[38:39], v[44:45] op_sel:[1,0] op_sel_hi:[0,1]
	v_pk_add_f32 v[44:45], v[44:45], v[44:45] op_sel:[0,1] op_sel_hi:[0,1]
	v_pk_mul_f32 v[46:47], v[50:51], v[44:45]
	v_pk_add_f32 v[42:43], v[42:43], v[42:43] op_sel:[0,1] op_sel_hi:[0,1] neg_lo:[0,1] neg_hi:[0,1]
	v_pk_fma_f32 v[48:49], v[50:51], v[42:43], v[46:47] op_sel:[0,0,1] op_sel_hi:[1,1,0] neg_lo:[0,0,1] neg_hi:[0,0,1]
	v_pk_fma_f32 v[46:47], v[50:51], v[42:43], v[46:47] op_sel:[0,0,1] op_sel_hi:[1,1,0]
	v_pk_mul_f32 v[44:45], v[38:39], v[44:45]
	v_mov_b32_e32 v49, v47
	v_pk_fma_f32 v[46:47], v[38:39], v[42:43], v[44:45] op_sel:[0,0,1] op_sel_hi:[1,1,0] neg_lo:[0,0,1] neg_hi:[0,0,1]
	v_pk_fma_f32 v[42:43], v[38:39], v[42:43], v[44:45] op_sel:[0,0,1] op_sel_hi:[1,1,0]
	v_mov_b32_e32 v44, v46
	v_mov_b32_e32 v45, v43
	v_pk_mul_f32 v[42:43], v[52:53], v[42:43] op_sel:[1,1] op_sel_hi:[0,1]
	v_pk_fma_f32 v[50:51], v[52:53], v[46:47], v[42:43] neg_lo:[0,0,1] neg_hi:[0,0,1]
	v_pk_fma_f32 v[42:43], v[52:53], v[46:47], v[42:43] op_sel_hi:[1,0,1]
	s_nop 0
	v_mov_b32_e32 v51, v43
	v_pk_mul_f32 v[42:43], v[38:39], v[44:45]
	v_pk_mul_f32 v[44:45], v[38:39], v[44:45] op_sel:[1,0] op_sel_hi:[0,1]
	v_pk_add_f32 v[44:45], v[44:45], v[44:45] op_sel:[0,1] op_sel_hi:[0,1]
	v_pk_mul_f32 v[46:47], v[54:55], v[44:45]
	v_pk_add_f32 v[42:43], v[42:43], v[42:43] op_sel:[0,1] op_sel_hi:[0,1] neg_lo:[0,1] neg_hi:[0,1]
	v_pk_fma_f32 v[52:53], v[54:55], v[42:43], v[46:47] op_sel:[0,0,1] op_sel_hi:[1,1,0] neg_lo:[0,0,1] neg_hi:[0,0,1]
	v_pk_fma_f32 v[46:47], v[54:55], v[42:43], v[46:47] op_sel:[0,0,1] op_sel_hi:[1,1,0]
	v_pk_mul_f32 v[44:45], v[38:39], v[44:45]
	v_mov_b32_e32 v53, v47
	v_pk_fma_f32 v[46:47], v[38:39], v[42:43], v[44:45] op_sel:[0,0,1] op_sel_hi:[1,1,0] neg_lo:[0,0,1] neg_hi:[0,0,1]
	v_pk_fma_f32 v[42:43], v[38:39], v[42:43], v[44:45] op_sel:[0,0,1] op_sel_hi:[1,1,0]
	v_mov_b32_e32 v44, v46
	v_mov_b32_e32 v45, v43
	v_pk_mul_f32 v[42:43], v[56:57], v[42:43] op_sel:[1,1] op_sel_hi:[0,1]
	v_pk_fma_f32 v[54:55], v[56:57], v[46:47], v[42:43] neg_lo:[0,0,1] neg_hi:[0,0,1]
	v_pk_fma_f32 v[42:43], v[56:57], v[46:47], v[42:43] op_sel_hi:[1,0,1]
	s_nop 0
	v_mov_b32_e32 v55, v43
	v_pk_mul_f32 v[42:43], v[38:39], v[44:45]
	v_pk_mul_f32 v[44:45], v[38:39], v[44:45] op_sel:[1,0] op_sel_hi:[0,1]
	v_pk_add_f32 v[44:45], v[44:45], v[44:45] op_sel:[0,1] op_sel_hi:[0,1]
	v_pk_mul_f32 v[46:47], v[58:59], v[44:45]
	v_pk_add_f32 v[42:43], v[42:43], v[42:43] op_sel:[0,1] op_sel_hi:[0,1] neg_lo:[0,1] neg_hi:[0,1]
	v_pk_fma_f32 v[56:57], v[58:59], v[42:43], v[46:47] op_sel:[0,0,1] op_sel_hi:[1,1,0] neg_lo:[0,0,1] neg_hi:[0,0,1]
	v_pk_fma_f32 v[46:47], v[58:59], v[42:43], v[46:47] op_sel:[0,0,1] op_sel_hi:[1,1,0]
	v_pk_mul_f32 v[44:45], v[38:39], v[44:45]
	v_mov_b32_e32 v57, v47
	v_pk_fma_f32 v[46:47], v[38:39], v[42:43], v[44:45] op_sel:[0,0,1] op_sel_hi:[1,1,0] neg_lo:[0,0,1] neg_hi:[0,0,1]
	v_pk_fma_f32 v[42:43], v[38:39], v[42:43], v[44:45] op_sel:[0,0,1] op_sel_hi:[1,1,0]
	v_mov_b32_e32 v44, v46
	v_mov_b32_e32 v45, v43
	v_pk_mul_f32 v[42:43], v[60:61], v[42:43] op_sel:[1,1] op_sel_hi:[0,1]
	v_pk_fma_f32 v[58:59], v[60:61], v[46:47], v[42:43] neg_lo:[0,0,1] neg_hi:[0,0,1]
	v_pk_fma_f32 v[42:43], v[60:61], v[46:47], v[42:43] op_sel_hi:[1,0,1]
	s_nop 0
	v_mov_b32_e32 v59, v43
	v_pk_mul_f32 v[42:43], v[38:39], v[44:45]
	v_pk_mul_f32 v[44:45], v[38:39], v[44:45] op_sel:[1,0] op_sel_hi:[0,1]
	v_pk_add_f32 v[44:45], v[44:45], v[44:45] op_sel:[0,1] op_sel_hi:[0,1]
	v_pk_mul_f32 v[46:47], v[62:63], v[44:45]
	v_pk_add_f32 v[42:43], v[42:43], v[42:43] op_sel:[0,1] op_sel_hi:[0,1] neg_lo:[0,1] neg_hi:[0,1]
	v_pk_fma_f32 v[60:61], v[62:63], v[42:43], v[46:47] op_sel:[0,0,1] op_sel_hi:[1,1,0] neg_lo:[0,0,1] neg_hi:[0,0,1]
	v_pk_fma_f32 v[46:47], v[62:63], v[42:43], v[46:47] op_sel:[0,0,1] op_sel_hi:[1,1,0]
	v_pk_mul_f32 v[44:45], v[38:39], v[44:45]
	v_mov_b32_e32 v61, v47
	v_pk_fma_f32 v[46:47], v[38:39], v[42:43], v[44:45] op_sel:[0,0,1] op_sel_hi:[1,1,0] neg_lo:[0,0,1] neg_hi:[0,0,1]
	v_pk_fma_f32 v[42:43], v[38:39], v[42:43], v[44:45] op_sel:[0,0,1] op_sel_hi:[1,1,0]
	v_mov_b32_e32 v44, v46
	v_mov_b32_e32 v45, v43
	v_pk_mul_f32 v[42:43], v[64:65], v[42:43] op_sel:[1,1] op_sel_hi:[0,1]
	v_pk_fma_f32 v[62:63], v[64:65], v[46:47], v[42:43] neg_lo:[0,0,1] neg_hi:[0,0,1]
	v_pk_fma_f32 v[42:43], v[64:65], v[46:47], v[42:43] op_sel_hi:[1,0,1]
	s_nop 0
	v_mov_b32_e32 v63, v43
	v_pk_mul_f32 v[42:43], v[38:39], v[44:45]
	v_pk_mul_f32 v[44:45], v[38:39], v[44:45] op_sel:[1,0] op_sel_hi:[0,1]
	v_pk_add_f32 v[44:45], v[44:45], v[44:45] op_sel:[0,1] op_sel_hi:[0,1]
	v_pk_mul_f32 v[46:47], v[66:67], v[44:45]
	v_pk_add_f32 v[42:43], v[42:43], v[42:43] op_sel:[0,1] op_sel_hi:[0,1] neg_lo:[0,1] neg_hi:[0,1]
	v_pk_fma_f32 v[64:65], v[66:67], v[42:43], v[46:47] op_sel:[0,0,1] op_sel_hi:[1,1,0] neg_lo:[0,0,1] neg_hi:[0,0,1]
	v_pk_fma_f32 v[46:47], v[66:67], v[42:43], v[46:47] op_sel:[0,0,1] op_sel_hi:[1,1,0]
	v_pk_mul_f32 v[42:43], v[38:39], v[42:43]
	v_mov_b32_e32 v65, v47
	v_pk_fma_f32 v[46:47], v[38:39], v[44:45], v[42:43] op_sel:[0,0,1] op_sel_hi:[1,1,0] neg_lo:[1,0,0] neg_hi:[1,0,0]
	v_pk_fma_f32 v[42:43], v[38:39], v[44:45], v[42:43] op_sel:[0,0,1] op_sel_hi:[1,1,0]
	v_mov_b32_e32 v45, v47
	v_mov_b32_e32 v44, v42
	v_pk_mul_f32 v[66:67], v[68:69], v[42:43] op_sel:[1,0] op_sel_hi:[0,0]
	v_pk_mov_b32 v[42:43], v[46:47], v[42:43] op_sel:[1,0]
	v_pk_fma_f32 v[156:157], v[68:69], v[46:47], v[66:67] op_sel:[0,1,0] neg_lo:[0,0,1] neg_hi:[0,0,1]
	v_pk_mul_f32 v[42:43], v[38:39], v[42:43]
	v_pk_mul_f32 v[38:39], v[38:39], v[44:45]
	v_pk_fma_f32 v[46:47], v[68:69], v[46:47], v[66:67] op_sel:[0,1,0]
	v_pk_add_f32 v[38:39], v[38:39], v[38:39] op_sel:[1,0] op_sel_hi:[1,0]
	v_pk_add_f32 v[42:43], v[42:43], v[42:43] op_sel:[0,1] op_sel_hi:[0,1] neg_lo:[0,1] neg_hi:[0,1]
	v_pk_mul_f32 v[38:39], v[146:147], v[38:39] op_sel:[1,0] op_sel_hi:[0,1]
	v_mov_b32_e32 v157, v47
	v_pk_fma_f32 v[44:45], v[146:147], v[42:43], v[38:39] neg_lo:[0,0,1] neg_hi:[0,0,1]
	v_pk_fma_f32 v[38:39], v[146:147], v[42:43], v[38:39]
	v_pk_add_f32 v[46:47], v[148:149], v[62:63] neg_lo:[0,1] neg_hi:[0,1]
	v_mov_b32_e32 v45, v39
	v_pk_add_f32 v[38:39], v[40:41], v[54:55]
	v_pk_add_f32 v[40:41], v[40:41], v[54:55] neg_lo:[0,1] neg_hi:[0,1]
	v_pk_add_f32 v[42:43], v[148:149], v[62:63]
	v_xor_b32_e32 v55, 0x80000000, v46
	v_mov_b32_e32 v54, v47
	v_pk_add_f32 v[46:47], v[38:39], v[42:43]
	v_pk_add_f32 v[62:63], v[40:41], v[54:55]
	v_pk_add_f32 v[38:39], v[38:39], v[42:43] neg_lo:[0,1] neg_hi:[0,1]
	v_pk_add_f32 v[40:41], v[40:41], v[54:55] neg_lo:[0,1] neg_hi:[0,1]
	v_pk_add_f32 v[42:43], v[150:151], v[56:57]
	v_pk_add_f32 v[54:55], v[150:151], v[56:57] neg_lo:[0,1] neg_hi:[0,1]
	v_pk_add_f32 v[56:57], v[48:49], v[64:65]
	v_pk_add_f32 v[48:49], v[48:49], v[64:65] neg_lo:[0,1] neg_hi:[0,1]
	s_nop 0
	v_xor_b32_e32 v65, 0x80000000, v48
	v_mov_b32_e32 v64, v49
	v_pk_add_f32 v[66:67], v[54:55], v[64:65]
	v_pk_add_f32 v[54:55], v[54:55], v[64:65] neg_lo:[0,1] neg_hi:[0,1]
	v_pk_add_f32 v[64:65], v[50:51], v[156:157]
	v_pk_add_f32 v[50:51], v[50:51], v[156:157] neg_lo:[0,1] neg_hi:[0,1]
	v_pk_add_f32 v[48:49], v[42:43], v[56:57]
	v_pk_add_f32 v[42:43], v[42:43], v[56:57] neg_lo:[0,1] neg_hi:[0,1]
	v_pk_add_f32 v[56:57], v[154:155], v[58:59]
	v_pk_add_f32 v[58:59], v[154:155], v[58:59] neg_lo:[0,1] neg_hi:[0,1]
	v_xor_b32_e32 v69, 0x80000000, v50
	v_mov_b32_e32 v68, v51
	v_pk_add_f32 v[146:147], v[58:59], v[68:69]
	v_pk_add_f32 v[58:59], v[58:59], v[68:69] neg_lo:[0,1] neg_hi:[0,1]
	v_pk_add_f32 v[68:69], v[52:53], v[44:45]
	v_pk_add_f32 v[44:45], v[52:53], v[44:45] neg_lo:[0,1] neg_hi:[0,1]
	v_pk_add_f32 v[50:51], v[56:57], v[64:65]
	v_pk_add_f32 v[56:57], v[56:57], v[64:65] neg_lo:[0,1] neg_hi:[0,1]
	v_pk_add_f32 v[64:65], v[152:153], v[60:61]
	v_pk_add_f32 v[60:61], v[152:153], v[60:61] neg_lo:[0,1] neg_hi:[0,1]
	v_xor_b32_e32 v53, 0x80000000, v44
	v_mov_b32_e32 v52, v45
	v_pk_add_f32 v[148:149], v[60:61], v[52:53]
	v_pk_add_f32 v[52:53], v[60:61], v[52:53] neg_lo:[0,1] neg_hi:[0,1]
	v_pk_mul_f32 v[60:61], v[66:67], s[8:9] op_sel_hi:[1,0]
	v_pk_add_f32 v[44:45], v[64:65], v[68:69]
	v_pk_add_f32 v[64:65], v[64:65], v[68:69] neg_lo:[0,1] neg_hi:[0,1]
	v_pk_fma_f32 v[68:69], v[66:67], s[10:11], v[60:61] op_sel:[0,0,1] op_sel_hi:[1,0,0]
	v_pk_fma_f32 v[60:61], v[66:67], s[10:11], v[60:61] op_sel:[0,0,1] op_sel_hi:[1,0,0] neg_lo:[0,0,1] neg_hi:[0,0,1]
	s_nop 0
	v_mov_b32_e32 v69, v61
	v_pk_mul_f32 v[60:61], v[146:147], s[12:13] op_sel_hi:[1,0]
	s_nop 0
	v_pk_fma_f32 v[66:67], v[146:147], s[12:13], v[60:61] op_sel:[0,0,1] op_sel_hi:[1,0,0]
	v_pk_fma_f32 v[60:61], v[146:147], s[12:13], v[60:61] op_sel_hi:[1,0,0] neg_lo:[0,0,1] neg_hi:[0,0,1]
	v_pk_mul_f32 v[146:147], v[148:149], s[10:11] op_sel_hi:[1,0]
	v_mov_b32_e32 v67, v61
	v_pk_fma_f32 v[150:151], v[148:149], s[8:9], v[146:147] op_sel:[0,0,1] op_sel_hi:[1,0,0]
	v_pk_fma_f32 v[146:147], v[148:149], s[8:9], v[146:147] op_sel:[0,0,1] op_sel_hi:[1,0,0] neg_lo:[0,0,1] neg_hi:[0,0,1]
	s_nop 0
	v_mov_b32_e32 v151, v147
	v_pk_mul_f32 v[146:147], v[42:43], s[12:13] op_sel_hi:[1,0]
	v_pk_add_f32 v[60:61], v[68:69], v[150:151]
	v_pk_fma_f32 v[148:149], v[42:43], s[12:13], v[146:147] op_sel:[0,0,1] op_sel_hi:[1,0,0]
	v_pk_fma_f32 v[42:43], v[42:43], s[12:13], v[146:147] op_sel_hi:[1,0,0] neg_lo:[0,0,1] neg_hi:[0,0,1]
	v_pk_fma_f32 v[146:147], v[56:57], 0, v[56:57] op_sel:[0,0,1] op_sel_hi:[1,0,0]
	v_pk_fma_f32 v[56:57], v[56:57], 0, v[56:57] op_sel:[0,0,1] op_sel_hi:[1,0,0] neg_lo:[0,0,1] neg_hi:[0,0,1]
	v_mov_b32_e32 v149, v43
	v_mov_b32_e32 v147, v57
	v_pk_mul_f32 v[56:57], v[64:65], s[14:15] op_sel_hi:[1,0]
	s_nop 0
	v_pk_fma_f32 v[152:153], v[64:65], s[14:15], v[56:57] op_sel:[0,0,1] op_sel_hi:[1,0,0] neg_lo:[0,0,1] neg_hi:[0,0,1]
	v_pk_fma_f32 v[56:57], v[64:65], s[14:15], v[56:57] op_sel_hi:[1,0,0]
	s_nop 0
	v_mov_b32_e32 v153, v57
	v_pk_mul_f32 v[56:57], v[54:55], s[10:11] op_sel_hi:[1,0]
	v_pk_add_f32 v[42:43], v[148:149], v[152:153]
	v_pk_fma_f32 v[64:65], v[54:55], s[8:9], v[56:57] op_sel:[0,0,1] op_sel_hi:[1,0,0]
	v_pk_fma_f32 v[54:55], v[54:55], s[8:9], v[56:57] op_sel:[0,0,1] op_sel_hi:[1,0,0] neg_lo:[0,0,1] neg_hi:[0,0,1]
	s_nop 0
	v_mov_b32_e32 v65, v55
	v_pk_mul_f32 v[54:55], v[58:59], s[14:15] op_sel_hi:[1,0]
	s_nop 0
	v_pk_fma_f32 v[56:57], v[58:59], s[14:15], v[54:55] op_sel:[0,0,1] op_sel_hi:[1,0,0] neg_lo:[0,0,1] neg_hi:[0,0,1]
	v_pk_fma_f32 v[54:55], v[58:59], s[14:15], v[54:55] op_sel_hi:[1,0,0]
	s_nop 0
	v_mov_b32_e32 v57, v55
	v_pk_mul_f32 v[54:55], v[52:53], s[8:9] op_sel:[1,0]
	s_nop 0
	v_pk_fma_f32 v[52:53], v[52:53], s[38:39], v[54:55] op_sel_hi:[0,1,1] neg_lo:[0,0,1] neg_hi:[0,0,1]
	v_pk_add_f32 v[54:55], v[46:47], v[50:51]
	v_pk_add_f32 v[46:47], v[46:47], v[50:51] neg_lo:[0,1] neg_hi:[0,1]
	v_pk_add_f32 v[50:51], v[48:49], v[44:45]
	v_pk_add_f32 v[44:45], v[48:49], v[44:45] neg_lo:[0,1] neg_hi:[0,1]
	s_nop 0
	v_xor_b32_e32 v49, 0x80000000, v44
	v_mov_b32_e32 v48, v45
	v_pk_add_f32 v[44:45], v[54:55], v[50:51]
	v_pk_add_f32 v[58:59], v[46:47], v[48:49]
	v_pk_add_f32 v[50:51], v[54:55], v[50:51] neg_lo:[0,1] neg_hi:[0,1]
	v_pk_add_f32 v[46:47], v[46:47], v[48:49] neg_lo:[0,1] neg_hi:[0,1]
	v_pk_add_f32 v[48:49], v[62:63], v[66:67]
	v_pk_add_f32 v[54:55], v[62:63], v[66:67] neg_lo:[0,1] neg_hi:[0,1]
	v_pk_add_f32 v[62:63], v[68:69], v[150:151] neg_lo:[0,1] neg_hi:[0,1]
	s_nop 0
	v_xor_b32_e32 v67, 0x80000000, v62
	v_mov_b32_e32 v66, v63
	v_pk_add_f32 v[62:63], v[48:49], v[60:61]
	v_pk_add_f32 v[68:69], v[54:55], v[66:67]
	v_pk_add_f32 v[48:49], v[48:49], v[60:61] neg_lo:[0,1] neg_hi:[0,1]
	v_pk_add_f32 v[54:55], v[54:55], v[66:67] neg_lo:[0,1] neg_hi:[0,1]
	v_pk_add_f32 v[60:61], v[38:39], v[146:147]
	v_pk_add_f32 v[66:67], v[148:149], v[152:153] neg_lo:[0,1] neg_hi:[0,1]
	v_pk_add_f32 v[38:39], v[38:39], v[146:147] neg_lo:[0,1] neg_hi:[0,1]
	v_xor_b32_e32 v147, 0x80000000, v66
	v_mov_b32_e32 v146, v67
	v_pk_add_f32 v[66:67], v[60:61], v[42:43]
	v_pk_add_f32 v[42:43], v[60:61], v[42:43] neg_lo:[0,1] neg_hi:[0,1]
	v_pk_add_f32 v[60:61], v[40:41], v[56:57]
	v_pk_add_f32 v[40:41], v[40:41], v[56:57] neg_lo:[0,1] neg_hi:[0,1]
	v_pk_add_f32 v[56:57], v[64:65], v[52:53]
	v_pk_add_f32 v[52:53], v[64:65], v[52:53] neg_lo:[0,1] neg_hi:[0,1]
	v_pk_add_f32 v[148:149], v[38:39], v[146:147]
	v_xor_b32_e32 v65, 0x80000000, v52
	v_mov_b32_e32 v64, v53
	v_pk_add_f32 v[38:39], v[38:39], v[146:147] neg_lo:[0,1] neg_hi:[0,1]
	v_pk_add_f32 v[52:53], v[60:61], v[56:57]
	v_pk_add_f32 v[146:147], v[40:41], v[64:65]
	v_pk_add_f32 v[56:57], v[60:61], v[56:57] neg_lo:[0,1] neg_hi:[0,1]
	v_pk_add_f32 v[40:41], v[40:41], v[64:65] neg_lo:[0,1] neg_hi:[0,1]
	ds_write_b64 v86, v[44:45]
	ds_write_b64 v87, v[58:59] offset:512
	ds_write_b64 v88, v[50:51] offset:1024
	ds_write_b64 v89, v[46:47] offset:1536
	ds_write_b64 v90, v[62:63] offset:128
	ds_write_b64 v91, v[68:69] offset:640
	ds_write_b64 v92, v[48:49] offset:1152
	ds_write_b64 v93, v[54:55] offset:1664
	ds_write_b64 v94, v[66:67] offset:256
	ds_write_b64 v95, v[148:149] offset:768
	ds_write_b64 v96, v[42:43] offset:1280
	ds_write_b64 v97, v[38:39] offset:1792
	ds_write_b64 v98, v[52:53] offset:384
	ds_write_b64 v99, v[146:147] offset:896
	ds_write_b64 v100, v[56:57] offset:1408
	ds_write_b64 v101, v[40:41] offset:1920
	s_waitcnt lgkmcnt(0)
	s_barrier
	ds_read_b64 v[38:39], v144
	ds_read_b64 v[40:41], v70
	ds_read_b64 v[42:43], v71 offset:4096
	ds_read_b64 v[44:45], v72 offset:8192
	ds_read_b64 v[46:47], v73 offset:12288
	ds_read_b64 v[48:49], v74 offset:16384
	ds_read_b64 v[50:51], v75 offset:20480
	ds_read_b64 v[52:53], v76 offset:24576
	ds_read_b64 v[54:55], v77 offset:28672
	ds_read_b64 v[56:57], v78 offset:32768
	ds_read_b64 v[58:59], v79 offset:36864
	ds_read_b64 v[60:61], v80 offset:40960
	ds_read_b64 v[62:63], v81 offset:45056
	ds_read_b64 v[64:65], v82 offset:49152
	ds_read_b64 v[66:67], v83 offset:53248
	ds_read_b64 v[68:69], v84 offset:57344
	ds_read_b64 v[146:147], v85 offset:61440
	s_waitcnt lgkmcnt(14)
	v_pk_mul_f32 v[148:149], v[38:39], v[42:43] op_sel:[1,1] op_sel_hi:[0,1]
	v_pk_fma_f32 v[150:151], v[38:39], v[42:43], v[148:149] neg_lo:[0,0,1] neg_hi:[0,0,1]
	v_pk_fma_f32 v[42:43], v[38:39], v[42:43], v[148:149] op_sel_hi:[1,0,1]
	s_waitcnt lgkmcnt(0)
	v_mov_b32_e32 v151, v43
	v_pk_mul_f32 v[42:43], v[38:39], v[38:39] op_sel:[1,1] op_sel_hi:[1,0]
	s_barrier
	v_pk_fma_f32 v[148:149], v[38:39], v[38:39], v[42:43] op_sel_hi:[1,0,1] neg_lo:[0,0,1] neg_hi:[0,0,1]
	v_pk_fma_f32 v[42:43], v[38:39], v[38:39], v[42:43] op_sel_hi:[1,0,1]
	v_mov_b32_e32 v152, v148
	v_mov_b32_e32 v153, v43
	v_pk_mul_f32 v[42:43], v[42:43], v[44:45] op_sel:[1,1] op_sel_hi:[1,0]
	s_nop 0
	v_pk_fma_f32 v[154:155], v[148:149], v[44:45], v[42:43] neg_lo:[0,0,1] neg_hi:[0,0,1]
	v_pk_fma_f32 v[42:43], v[148:149], v[44:45], v[42:43] op_sel_hi:[0,1,1]
	v_pk_mul_f32 v[44:45], v[38:39], v[152:153] op_sel:[1,0] op_sel_hi:[0,1]
	v_mov_b32_e32 v155, v43
	v_pk_mul_f32 v[42:43], v[38:39], v[152:153]
	v_pk_add_f32 v[44:45], v[44:45], v[44:45] op_sel:[0,1] op_sel_hi:[0,1]
	v_pk_mul_f32 v[148:149], v[46:47], v[44:45]
	v_pk_add_f32 v[42:43], v[42:43], v[42:43] op_sel:[0,1] op_sel_hi:[0,1] neg_lo:[0,1] neg_hi:[0,1]
	v_pk_fma_f32 v[152:153], v[46:47], v[42:43], v[148:149] op_sel:[0,0,1] op_sel_hi:[1,1,0] neg_lo:[0,0,1] neg_hi:[0,0,1]
	v_pk_fma_f32 v[46:47], v[46:47], v[42:43], v[148:149] op_sel:[0,0,1] op_sel_hi:[1,1,0]
	v_pk_mul_f32 v[44:45], v[38:39], v[44:45]
	v_mov_b32_e32 v153, v47
	v_pk_fma_f32 v[46:47], v[38:39], v[42:43], v[44:45] op_sel:[0,0,1] op_sel_hi:[1,1,0] neg_lo:[0,0,1] neg_hi:[0,0,1]
	v_pk_fma_f32 v[42:43], v[38:39], v[42:43], v[44:45] op_sel:[0,0,1] op_sel_hi:[1,1,0]
	v_mov_b32_e32 v44, v46
	v_mov_b32_e32 v45, v43
	v_pk_mul_f32 v[42:43], v[48:49], v[42:43] op_sel:[1,1] op_sel_hi:[0,1]
	v_pk_fma_f32 v[148:149], v[48:49], v[46:47], v[42:43] neg_lo:[0,0,1] neg_hi:[0,0,1]
	v_pk_fma_f32 v[42:43], v[48:49], v[46:47], v[42:43] op_sel_hi:[1,0,1]
	s_nop 0
	v_mov_b32_e32 v149, v43
	v_pk_mul_f32 v[42:43], v[38:39], v[44:45]
	v_pk_mul_f32 v[44:45], v[38:39], v[44:45] op_sel:[1,0] op_sel_hi:[0,1]
	v_pk_add_f32 v[44:45], v[44:45], v[44:45] op_sel:[0,1] op_sel_hi:[0,1]
	v_pk_mul_f32 v[46:47], v[50:51], v[44:45]
	v_pk_add_f32 v[42:43], v[42:43], v[42:43] op_sel:[0,1] op_sel_hi:[0,1] neg_lo:[0,1] neg_hi:[0,1]
	v_pk_fma_f32 v[48:49], v[50:51], v[42:43], v[46:47] op_sel:[0,0,1] op_sel_hi:[1,1,0] neg_lo:[0,0,1] neg_hi:[0,0,1]
	v_pk_fma_f32 v[46:47], v[50:51], v[42:43], v[46:47] op_sel:[0,0,1] op_sel_hi:[1,1,0]
	v_pk_mul_f32 v[44:45], v[38:39], v[44:45]
	v_mov_b32_e32 v49, v47
	v_pk_fma_f32 v[46:47], v[38:39], v[42:43], v[44:45] op_sel:[0,0,1] op_sel_hi:[1,1,0] neg_lo:[0,0,1] neg_hi:[0,0,1]
	v_pk_fma_f32 v[42:43], v[38:39], v[42:43], v[44:45] op_sel:[0,0,1] op_sel_hi:[1,1,0]
	v_mov_b32_e32 v44, v46
	v_mov_b32_e32 v45, v43
	v_pk_mul_f32 v[42:43], v[52:53], v[42:43] op_sel:[1,1] op_sel_hi:[0,1]
	v_pk_fma_f32 v[50:51], v[52:53], v[46:47], v[42:43] neg_lo:[0,0,1] neg_hi:[0,0,1]
	v_pk_fma_f32 v[42:43], v[52:53], v[46:47], v[42:43] op_sel_hi:[1,0,1]
	s_nop 0
	v_mov_b32_e32 v51, v43
	v_pk_mul_f32 v[42:43], v[38:39], v[44:45]
	v_pk_mul_f32 v[44:45], v[38:39], v[44:45] op_sel:[1,0] op_sel_hi:[0,1]
	v_pk_add_f32 v[44:45], v[44:45], v[44:45] op_sel:[0,1] op_sel_hi:[0,1]
	v_pk_mul_f32 v[46:47], v[54:55], v[44:45]
	v_pk_add_f32 v[42:43], v[42:43], v[42:43] op_sel:[0,1] op_sel_hi:[0,1] neg_lo:[0,1] neg_hi:[0,1]
	v_pk_fma_f32 v[52:53], v[54:55], v[42:43], v[46:47] op_sel:[0,0,1] op_sel_hi:[1,1,0] neg_lo:[0,0,1] neg_hi:[0,0,1]
	v_pk_fma_f32 v[46:47], v[54:55], v[42:43], v[46:47] op_sel:[0,0,1] op_sel_hi:[1,1,0]
	v_pk_mul_f32 v[44:45], v[38:39], v[44:45]
	v_mov_b32_e32 v53, v47
	v_pk_fma_f32 v[46:47], v[38:39], v[42:43], v[44:45] op_sel:[0,0,1] op_sel_hi:[1,1,0] neg_lo:[0,0,1] neg_hi:[0,0,1]
	v_pk_fma_f32 v[42:43], v[38:39], v[42:43], v[44:45] op_sel:[0,0,1] op_sel_hi:[1,1,0]
	v_mov_b32_e32 v44, v46
	v_mov_b32_e32 v45, v43
	v_pk_mul_f32 v[42:43], v[56:57], v[42:43] op_sel:[1,1] op_sel_hi:[0,1]
	v_pk_fma_f32 v[54:55], v[56:57], v[46:47], v[42:43] neg_lo:[0,0,1] neg_hi:[0,0,1]
	v_pk_fma_f32 v[42:43], v[56:57], v[46:47], v[42:43] op_sel_hi:[1,0,1]
	s_nop 0
	v_mov_b32_e32 v55, v43
	v_pk_mul_f32 v[42:43], v[38:39], v[44:45]
	v_pk_mul_f32 v[44:45], v[38:39], v[44:45] op_sel:[1,0] op_sel_hi:[0,1]
	v_pk_add_f32 v[44:45], v[44:45], v[44:45] op_sel:[0,1] op_sel_hi:[0,1]
	v_pk_mul_f32 v[46:47], v[58:59], v[44:45]
	v_pk_add_f32 v[42:43], v[42:43], v[42:43] op_sel:[0,1] op_sel_hi:[0,1] neg_lo:[0,1] neg_hi:[0,1]
	v_pk_fma_f32 v[56:57], v[58:59], v[42:43], v[46:47] op_sel:[0,0,1] op_sel_hi:[1,1,0] neg_lo:[0,0,1] neg_hi:[0,0,1]
	v_pk_fma_f32 v[46:47], v[58:59], v[42:43], v[46:47] op_sel:[0,0,1] op_sel_hi:[1,1,0]
	v_pk_mul_f32 v[44:45], v[38:39], v[44:45]
	v_mov_b32_e32 v57, v47
	v_pk_fma_f32 v[46:47], v[38:39], v[42:43], v[44:45] op_sel:[0,0,1] op_sel_hi:[1,1,0] neg_lo:[0,0,1] neg_hi:[0,0,1]
	v_pk_fma_f32 v[42:43], v[38:39], v[42:43], v[44:45] op_sel:[0,0,1] op_sel_hi:[1,1,0]
	v_mov_b32_e32 v44, v46
	v_mov_b32_e32 v45, v43
	v_pk_mul_f32 v[42:43], v[60:61], v[42:43] op_sel:[1,1] op_sel_hi:[0,1]
	v_pk_fma_f32 v[58:59], v[60:61], v[46:47], v[42:43] neg_lo:[0,0,1] neg_hi:[0,0,1]
	v_pk_fma_f32 v[42:43], v[60:61], v[46:47], v[42:43] op_sel_hi:[1,0,1]
	s_nop 0
	v_mov_b32_e32 v59, v43
	v_pk_mul_f32 v[42:43], v[38:39], v[44:45]
	v_pk_mul_f32 v[44:45], v[38:39], v[44:45] op_sel:[1,0] op_sel_hi:[0,1]
	v_pk_add_f32 v[44:45], v[44:45], v[44:45] op_sel:[0,1] op_sel_hi:[0,1]
	v_pk_mul_f32 v[46:47], v[62:63], v[44:45]
	v_pk_add_f32 v[42:43], v[42:43], v[42:43] op_sel:[0,1] op_sel_hi:[0,1] neg_lo:[0,1] neg_hi:[0,1]
	v_pk_fma_f32 v[60:61], v[62:63], v[42:43], v[46:47] op_sel:[0,0,1] op_sel_hi:[1,1,0] neg_lo:[0,0,1] neg_hi:[0,0,1]
	v_pk_fma_f32 v[46:47], v[62:63], v[42:43], v[46:47] op_sel:[0,0,1] op_sel_hi:[1,1,0]
	v_pk_mul_f32 v[44:45], v[38:39], v[44:45]
	v_mov_b32_e32 v61, v47
	v_pk_fma_f32 v[46:47], v[38:39], v[42:43], v[44:45] op_sel:[0,0,1] op_sel_hi:[1,1,0] neg_lo:[0,0,1] neg_hi:[0,0,1]
	v_pk_fma_f32 v[42:43], v[38:39], v[42:43], v[44:45] op_sel:[0,0,1] op_sel_hi:[1,1,0]
	v_mov_b32_e32 v44, v46
	v_mov_b32_e32 v45, v43
	v_pk_mul_f32 v[42:43], v[64:65], v[42:43] op_sel:[1,1] op_sel_hi:[0,1]
	v_pk_fma_f32 v[62:63], v[64:65], v[46:47], v[42:43] neg_lo:[0,0,1] neg_hi:[0,0,1]
	v_pk_fma_f32 v[42:43], v[64:65], v[46:47], v[42:43] op_sel_hi:[1,0,1]
	s_nop 0
	v_mov_b32_e32 v63, v43
	v_pk_mul_f32 v[42:43], v[38:39], v[44:45]
	v_pk_mul_f32 v[44:45], v[38:39], v[44:45] op_sel:[1,0] op_sel_hi:[0,1]
	v_pk_add_f32 v[44:45], v[44:45], v[44:45] op_sel:[0,1] op_sel_hi:[0,1]
	v_pk_mul_f32 v[46:47], v[66:67], v[44:45]
	v_pk_add_f32 v[42:43], v[42:43], v[42:43] op_sel:[0,1] op_sel_hi:[0,1] neg_lo:[0,1] neg_hi:[0,1]
	v_pk_fma_f32 v[64:65], v[66:67], v[42:43], v[46:47] op_sel:[0,0,1] op_sel_hi:[1,1,0] neg_lo:[0,0,1] neg_hi:[0,0,1]
	v_pk_fma_f32 v[46:47], v[66:67], v[42:43], v[46:47] op_sel:[0,0,1] op_sel_hi:[1,1,0]
	v_pk_mul_f32 v[42:43], v[38:39], v[42:43]
	v_mov_b32_e32 v65, v47
	v_pk_fma_f32 v[46:47], v[38:39], v[44:45], v[42:43] op_sel:[0,0,1] op_sel_hi:[1,1,0] neg_lo:[1,0,0] neg_hi:[1,0,0]
	v_pk_fma_f32 v[42:43], v[38:39], v[44:45], v[42:43] op_sel:[0,0,1] op_sel_hi:[1,1,0]
	v_mov_b32_e32 v45, v47
	v_mov_b32_e32 v44, v42
	v_pk_mul_f32 v[66:67], v[68:69], v[42:43] op_sel:[1,0] op_sel_hi:[0,0]
	v_pk_mov_b32 v[42:43], v[46:47], v[42:43] op_sel:[1,0]
	v_pk_fma_f32 v[156:157], v[68:69], v[46:47], v[66:67] op_sel:[0,1,0] neg_lo:[0,0,1] neg_hi:[0,0,1]
	v_pk_mul_f32 v[42:43], v[38:39], v[42:43]
	v_pk_mul_f32 v[38:39], v[38:39], v[44:45]
	v_pk_fma_f32 v[46:47], v[68:69], v[46:47], v[66:67] op_sel:[0,1,0]
	v_pk_add_f32 v[38:39], v[38:39], v[38:39] op_sel:[1,0] op_sel_hi:[1,0]
	v_pk_add_f32 v[42:43], v[42:43], v[42:43] op_sel:[0,1] op_sel_hi:[0,1] neg_lo:[0,1] neg_hi:[0,1]
	v_pk_mul_f32 v[38:39], v[146:147], v[38:39] op_sel:[1,0] op_sel_hi:[0,1]
	v_mov_b32_e32 v157, v47
	v_pk_fma_f32 v[44:45], v[146:147], v[42:43], v[38:39] neg_lo:[0,0,1] neg_hi:[0,0,1]
	v_pk_fma_f32 v[38:39], v[146:147], v[42:43], v[38:39]
	v_pk_add_f32 v[46:47], v[148:149], v[62:63] neg_lo:[0,1] neg_hi:[0,1]
	v_mov_b32_e32 v45, v39
	v_pk_add_f32 v[38:39], v[40:41], v[54:55]
	v_pk_add_f32 v[40:41], v[40:41], v[54:55] neg_lo:[0,1] neg_hi:[0,1]
	v_pk_add_f32 v[42:43], v[148:149], v[62:63]
	v_xor_b32_e32 v55, 0x80000000, v46
	v_mov_b32_e32 v54, v47
	v_pk_add_f32 v[46:47], v[38:39], v[42:43]
	v_pk_add_f32 v[62:63], v[40:41], v[54:55]
	v_pk_add_f32 v[38:39], v[38:39], v[42:43] neg_lo:[0,1] neg_hi:[0,1]
	v_pk_add_f32 v[40:41], v[40:41], v[54:55] neg_lo:[0,1] neg_hi:[0,1]
	v_pk_add_f32 v[42:43], v[150:151], v[56:57]
	v_pk_add_f32 v[54:55], v[150:151], v[56:57] neg_lo:[0,1] neg_hi:[0,1]
	v_pk_add_f32 v[56:57], v[48:49], v[64:65]
	v_pk_add_f32 v[48:49], v[48:49], v[64:65] neg_lo:[0,1] neg_hi:[0,1]
	s_nop 0
	v_xor_b32_e32 v65, 0x80000000, v48
	v_mov_b32_e32 v64, v49
	v_pk_add_f32 v[66:67], v[54:55], v[64:65]
	v_pk_add_f32 v[54:55], v[54:55], v[64:65] neg_lo:[0,1] neg_hi:[0,1]
	v_pk_add_f32 v[64:65], v[50:51], v[156:157]
	v_pk_add_f32 v[50:51], v[50:51], v[156:157] neg_lo:[0,1] neg_hi:[0,1]
	v_pk_add_f32 v[48:49], v[42:43], v[56:57]
	v_pk_add_f32 v[42:43], v[42:43], v[56:57] neg_lo:[0,1] neg_hi:[0,1]
	v_pk_add_f32 v[56:57], v[154:155], v[58:59]
	v_pk_add_f32 v[58:59], v[154:155], v[58:59] neg_lo:[0,1] neg_hi:[0,1]
	v_xor_b32_e32 v69, 0x80000000, v50
	v_mov_b32_e32 v68, v51
	v_pk_add_f32 v[146:147], v[58:59], v[68:69]
	v_pk_add_f32 v[58:59], v[58:59], v[68:69] neg_lo:[0,1] neg_hi:[0,1]
	v_pk_add_f32 v[68:69], v[52:53], v[44:45]
	v_pk_add_f32 v[44:45], v[52:53], v[44:45] neg_lo:[0,1] neg_hi:[0,1]
	v_pk_add_f32 v[50:51], v[56:57], v[64:65]
	v_pk_add_f32 v[56:57], v[56:57], v[64:65] neg_lo:[0,1] neg_hi:[0,1]
	v_pk_add_f32 v[64:65], v[152:153], v[60:61]
	v_pk_add_f32 v[60:61], v[152:153], v[60:61] neg_lo:[0,1] neg_hi:[0,1]
	v_xor_b32_e32 v53, 0x80000000, v44
	v_mov_b32_e32 v52, v45
	v_pk_add_f32 v[148:149], v[60:61], v[52:53]
	v_pk_add_f32 v[52:53], v[60:61], v[52:53] neg_lo:[0,1] neg_hi:[0,1]
	v_pk_mul_f32 v[60:61], v[66:67], s[8:9] op_sel_hi:[1,0]
	v_pk_add_f32 v[44:45], v[64:65], v[68:69]
	v_pk_add_f32 v[64:65], v[64:65], v[68:69] neg_lo:[0,1] neg_hi:[0,1]
	v_pk_fma_f32 v[68:69], v[66:67], s[10:11], v[60:61] op_sel:[0,0,1] op_sel_hi:[1,0,0]
	v_pk_fma_f32 v[60:61], v[66:67], s[10:11], v[60:61] op_sel:[0,0,1] op_sel_hi:[1,0,0] neg_lo:[0,0,1] neg_hi:[0,0,1]
	s_nop 0
	v_mov_b32_e32 v69, v61
	v_pk_mul_f32 v[60:61], v[146:147], s[12:13] op_sel_hi:[1,0]
	s_nop 0
	v_pk_fma_f32 v[66:67], v[146:147], s[12:13], v[60:61] op_sel:[0,0,1] op_sel_hi:[1,0,0]
	v_pk_fma_f32 v[60:61], v[146:147], s[12:13], v[60:61] op_sel_hi:[1,0,0] neg_lo:[0,0,1] neg_hi:[0,0,1]
	v_pk_mul_f32 v[146:147], v[148:149], s[10:11] op_sel_hi:[1,0]
	v_mov_b32_e32 v67, v61
	v_pk_fma_f32 v[150:151], v[148:149], s[8:9], v[146:147] op_sel:[0,0,1] op_sel_hi:[1,0,0]
	v_pk_fma_f32 v[146:147], v[148:149], s[8:9], v[146:147] op_sel:[0,0,1] op_sel_hi:[1,0,0] neg_lo:[0,0,1] neg_hi:[0,0,1]
	s_nop 0
	v_mov_b32_e32 v151, v147
	v_pk_mul_f32 v[146:147], v[42:43], s[12:13] op_sel_hi:[1,0]
	v_pk_add_f32 v[60:61], v[68:69], v[150:151]
	v_pk_fma_f32 v[148:149], v[42:43], s[12:13], v[146:147] op_sel:[0,0,1] op_sel_hi:[1,0,0]
	v_pk_fma_f32 v[42:43], v[42:43], s[12:13], v[146:147] op_sel_hi:[1,0,0] neg_lo:[0,0,1] neg_hi:[0,0,1]
	v_pk_fma_f32 v[146:147], v[56:57], 0, v[56:57] op_sel:[0,0,1] op_sel_hi:[1,0,0]
	v_pk_fma_f32 v[56:57], v[56:57], 0, v[56:57] op_sel:[0,0,1] op_sel_hi:[1,0,0] neg_lo:[0,0,1] neg_hi:[0,0,1]
	v_mov_b32_e32 v149, v43
	v_mov_b32_e32 v147, v57
	v_pk_mul_f32 v[56:57], v[64:65], s[14:15] op_sel_hi:[1,0]
	s_nop 0
	v_pk_fma_f32 v[152:153], v[64:65], s[14:15], v[56:57] op_sel:[0,0,1] op_sel_hi:[1,0,0] neg_lo:[0,0,1] neg_hi:[0,0,1]
	v_pk_fma_f32 v[56:57], v[64:65], s[14:15], v[56:57] op_sel_hi:[1,0,0]
	s_nop 0
	v_mov_b32_e32 v153, v57
	v_pk_mul_f32 v[56:57], v[54:55], s[10:11] op_sel_hi:[1,0]
	v_pk_add_f32 v[42:43], v[148:149], v[152:153]
	v_pk_fma_f32 v[64:65], v[54:55], s[8:9], v[56:57] op_sel:[0,0,1] op_sel_hi:[1,0,0]
	v_pk_fma_f32 v[54:55], v[54:55], s[8:9], v[56:57] op_sel:[0,0,1] op_sel_hi:[1,0,0] neg_lo:[0,0,1] neg_hi:[0,0,1]
	s_nop 0
	v_mov_b32_e32 v65, v55
	v_pk_mul_f32 v[54:55], v[58:59], s[14:15] op_sel_hi:[1,0]
	s_nop 0
	v_pk_fma_f32 v[56:57], v[58:59], s[14:15], v[54:55] op_sel:[0,0,1] op_sel_hi:[1,0,0] neg_lo:[0,0,1] neg_hi:[0,0,1]
	v_pk_fma_f32 v[54:55], v[58:59], s[14:15], v[54:55] op_sel_hi:[1,0,0]
	s_nop 0
	v_mov_b32_e32 v57, v55
	v_pk_mul_f32 v[54:55], v[52:53], s[8:9] op_sel:[1,0]
	s_nop 0
	v_pk_fma_f32 v[52:53], v[52:53], s[38:39], v[54:55] op_sel_hi:[0,1,1] neg_lo:[0,0,1] neg_hi:[0,0,1]
	v_pk_add_f32 v[54:55], v[46:47], v[50:51]
	v_pk_add_f32 v[46:47], v[46:47], v[50:51] neg_lo:[0,1] neg_hi:[0,1]
	v_pk_add_f32 v[50:51], v[48:49], v[44:45]
	v_pk_add_f32 v[44:45], v[48:49], v[44:45] neg_lo:[0,1] neg_hi:[0,1]
	s_nop 0
	v_xor_b32_e32 v49, 0x80000000, v44
	v_mov_b32_e32 v48, v45
	v_pk_add_f32 v[44:45], v[54:55], v[50:51]
	v_pk_add_f32 v[58:59], v[46:47], v[48:49]
	v_pk_add_f32 v[50:51], v[54:55], v[50:51] neg_lo:[0,1] neg_hi:[0,1]
	v_pk_add_f32 v[46:47], v[46:47], v[48:49] neg_lo:[0,1] neg_hi:[0,1]
	v_pk_add_f32 v[48:49], v[62:63], v[66:67]
	v_pk_add_f32 v[54:55], v[62:63], v[66:67] neg_lo:[0,1] neg_hi:[0,1]
	v_pk_add_f32 v[62:63], v[68:69], v[150:151] neg_lo:[0,1] neg_hi:[0,1]
	s_nop 0
	v_xor_b32_e32 v67, 0x80000000, v62
	v_mov_b32_e32 v66, v63
	v_pk_add_f32 v[62:63], v[48:49], v[60:61]
	v_pk_add_f32 v[68:69], v[54:55], v[66:67]
	v_pk_add_f32 v[48:49], v[48:49], v[60:61] neg_lo:[0,1] neg_hi:[0,1]
	v_pk_add_f32 v[54:55], v[54:55], v[66:67] neg_lo:[0,1] neg_hi:[0,1]
	v_pk_add_f32 v[60:61], v[38:39], v[146:147]
	v_pk_add_f32 v[66:67], v[148:149], v[152:153] neg_lo:[0,1] neg_hi:[0,1]
	v_pk_add_f32 v[38:39], v[38:39], v[146:147] neg_lo:[0,1] neg_hi:[0,1]
	v_xor_b32_e32 v147, 0x80000000, v66
	v_mov_b32_e32 v146, v67
	v_pk_add_f32 v[66:67], v[60:61], v[42:43]
	v_pk_add_f32 v[42:43], v[60:61], v[42:43] neg_lo:[0,1] neg_hi:[0,1]
	v_pk_add_f32 v[60:61], v[40:41], v[56:57]
	v_pk_add_f32 v[40:41], v[40:41], v[56:57] neg_lo:[0,1] neg_hi:[0,1]
	v_pk_add_f32 v[56:57], v[64:65], v[52:53]
	v_pk_add_f32 v[52:53], v[64:65], v[52:53] neg_lo:[0,1] neg_hi:[0,1]
	v_pk_add_f32 v[148:149], v[38:39], v[146:147]
	v_xor_b32_e32 v65, 0x80000000, v52
	v_mov_b32_e32 v64, v53
	v_pk_add_f32 v[38:39], v[38:39], v[146:147] neg_lo:[0,1] neg_hi:[0,1]
	v_pk_add_f32 v[52:53], v[60:61], v[56:57]
	v_pk_add_f32 v[146:147], v[40:41], v[64:65]
	v_pk_add_f32 v[56:57], v[60:61], v[56:57] neg_lo:[0,1] neg_hi:[0,1]
	v_pk_add_f32 v[40:41], v[40:41], v[64:65] neg_lo:[0,1] neg_hi:[0,1]
	ds_write_b64 v102, v[44:45]
	ds_write_b64 v103, v[58:59] offset:8192
	ds_write_b64 v104, v[50:51] offset:16384
	ds_write_b64 v105, v[46:47] offset:24576
	ds_write_b64 v106, v[62:63] offset:2048
	ds_write_b64 v107, v[68:69] offset:10240
	ds_write_b64 v108, v[48:49] offset:18432
	ds_write_b64 v109, v[54:55] offset:26624
	ds_write_b64 v110, v[66:67] offset:4096
	ds_write_b64 v111, v[148:149] offset:12288
	ds_write_b64 v112, v[42:43] offset:20480
	ds_write_b64 v113, v[38:39] offset:28672
	ds_write_b64 v114, v[52:53] offset:6144
	ds_write_b64 v115, v[146:147] offset:14336
	ds_write_b64 v116, v[56:57] offset:22528
	ds_write_b64 v117, v[40:41] offset:30720
	s_waitcnt lgkmcnt(0)
	s_barrier
	s_cbranch_scc1 .LBB0_305
	ds_read_b64 v[40:41], v70
	ds_read_b64 v[38:39], v78 offset:32768
	ds_read_b64 v[42:43], v118
	s_mul_i32 s11, s2, 33
	s_mul_hi_i32 s9, s2, 33
	s_add_u32 s18, s11, s3
	s_addc_u32 s19, s9, 0
	s_lshl_b64 s[18:19], s[18:19], 15
	s_add_u32 s28, s16, s18
	s_waitcnt lgkmcnt(0)
	v_pk_mul_f32 v[38:39], v[38:39], v[42:43]
	s_addc_u32 s29, s33, s19
	v_sub_f32_e32 v41, v38, v39
	v_add_f32_e32 v42, v40, v41
	v_lshl_add_u64 v[38:39], v[0:1], 2, s[28:29]
	global_store_dword v[38:39], v42, off sc1
	v_add_co_u32_e32 v42, vcc, s44, v38
	v_sub_f32_e32 v44, v40, v41
	s_nop 0
	v_addc_co_u32_e32 v43, vcc, 0, v39, vcc
	v_add_co_u32_e32 v40, vcc, s46, v38
	s_nop 1
	v_addc_co_u32_e32 v41, vcc, 0, v39, vcc
	global_store_dword v[40:41], v44, off offset:-4096 sc1
	ds_read_b64 v[44:45], v71 offset:4096
	ds_read_b64 v[46:47], v79 offset:36864
	ds_read_b64 v[48:49], v119
	s_waitcnt lgkmcnt(0)
	v_pk_mul_f32 v[46:47], v[46:47], v[48:49]
	s_nop 0
	v_sub_f32_e32 v45, v46, v47
	v_add_f32_e32 v46, v44, v45
	v_sub_f32_e32 v44, v44, v45
	global_store_dword v[38:39], v46, off offset:2048 sc1
	global_store_dword v[42:43], v44, off offset:2048 sc1
	ds_read_b64 v[42:43], v72 offset:8192
	ds_read_b64 v[44:45], v80 offset:40960
	ds_read_b64 v[46:47], v120
	s_waitcnt lgkmcnt(0)
	v_pk_mul_f32 v[44:45], v[44:45], v[46:47]
	s_nop 0
	v_sub_f32_e32 v43, v44, v45
	v_add_co_u32_e32 v44, vcc, s34, v38
	v_add_f32_e32 v48, v42, v43
	s_nop 0
	v_addc_co_u32_e32 v45, vcc, 0, v39, vcc
	v_add_co_u32_e32 v46, vcc, s15, v38
	v_sub_f32_e32 v42, v42, v43
	s_nop 0
	v_addc_co_u32_e32 v47, vcc, 0, v39, vcc
	global_store_dword v[46:47], v48, off offset:-4096 sc1
	global_store_dword v[40:41], v42, off sc1
	ds_read_b64 v[42:43], v73 offset:12288
	ds_read_b64 v[48:49], v81 offset:45056
	ds_read_b64 v[50:51], v121
	s_waitcnt lgkmcnt(0)
	v_pk_mul_f32 v[48:49], v[48:49], v[50:51]
	s_nop 0
	v_sub_f32_e32 v43, v48, v49
	v_add_f32_e32 v48, v42, v43
	v_sub_f32_e32 v42, v42, v43
	global_store_dword v[44:45], v48, off offset:2048 sc1
	global_store_dword v[40:41], v42, off offset:2048 sc1
	ds_read_b64 v[40:41], v74 offset:16384
	ds_read_b64 v[42:43], v82 offset:49152
	ds_read_b64 v[44:45], v122
	s_waitcnt lgkmcnt(0)
	v_pk_mul_f32 v[42:43], v[42:43], v[44:45]
	s_nop 0
	v_sub_f32_e32 v41, v42, v43
	v_add_f32_e32 v42, v40, v41
	global_store_dword v[46:47], v42, off sc1
	v_sub_f32_e32 v42, v40, v41
	v_add_co_u32_e32 v40, vcc, s45, v38
	s_nop 1
	v_addc_co_u32_e32 v41, vcc, 0, v39, vcc
	global_store_dword v[40:41], v42, off sc1
	ds_read_b64 v[42:43], v75 offset:20480
	ds_read_b64 v[44:45], v83 offset:53248
	ds_read_b64 v[48:49], v123
	s_waitcnt lgkmcnt(0)
	v_pk_mul_f32 v[44:45], v[44:45], v[48:49]
	s_nop 0
	v_sub_f32_e32 v43, v44, v45
	v_add_f32_e32 v44, v42, v43
	v_sub_f32_e32 v42, v42, v43
	global_store_dword v[46:47], v44, off offset:2048 sc1
	global_store_dword v[40:41], v42, off offset:2048 sc1
	ds_read_b64 v[40:41], v76 offset:24576
	ds_read_b64 v[42:43], v84 offset:57344
	ds_read_b64 v[44:45], v124
	s_waitcnt lgkmcnt(0)
	v_pk_mul_f32 v[42:43], v[42:43], v[44:45]
	s_nop 0
	v_sub_f32_e32 v41, v42, v43
	v_add_co_u32_e32 v42, vcc, 0x3000, v38
	v_add_f32_e32 v44, v40, v41
	s_nop 0
	v_addc_co_u32_e32 v43, vcc, 0, v39, vcc
	v_add_co_u32_e32 v38, vcc, 0x7000, v38
	v_sub_f32_e32 v40, v40, v41
	s_nop 0
	v_addc_co_u32_e32 v39, vcc, 0, v39, vcc
	global_store_dword v[42:43], v44, off sc1
	global_store_dword v[38:39], v40, off sc1
	ds_read_b64 v[38:39], v77 offset:28672
	ds_read_b64 v[40:41], v85 offset:61440
	ds_read_b64 v[44:45], v125
	s_waitcnt lgkmcnt(0)
	v_pk_mul_f32 v[40:41], v[40:41], v[44:45]
	s_nop 0
	v_sub_f32_e32 v39, v40, v41
	v_add_f32_e32 v40, v38, v39
	v_sub_f32_e32 v38, v38, v39
	global_store_dword v[42:43], v40, off offset:2048 sc1
	s_cbranch_execnz .LBB0_300
	s_branch .LBB0_306
.LBB0_305:
.LBB0_306:
	ds_read_b64 v[40:41], v70
	ds_read_b64 v[38:39], v78 offset:32768
	ds_read_b64 v[42:43], v118
	s_mul_hi_i32 s3, s2, 0x108000
	s_mul_i32 s2, s2, 0x108000
	s_add_u32 s2, s16, s2
	s_addc_u32 s3, s33, s3
	s_waitcnt lgkmcnt(0)
	v_pk_mul_f32 v[44:45], v[38:39], v[42:43] op_sel:[1,1] op_sel_hi:[1,0]
	s_add_u32 s28, s2, 0x100000
	v_pk_fma_f32 v[46:47], v[38:39], v[42:43], v[44:45] neg_lo:[0,0,1] neg_hi:[0,0,1]
	v_pk_fma_f32 v[38:39], v[38:39], v[42:43], v[44:45] op_sel_hi:[0,1,1]
	v_mov_b32_e32 v47, v39
	v_pk_add_f32 v[38:39], v[40:41], v[46:47]
	v_pk_add_f32 v[40:41], v[40:41], v[46:47] neg_lo:[0,1] neg_hi:[0,1]
	ds_read_b64 v[44:45], v71 offset:4096
	ds_read_b64 v[42:43], v79 offset:36864
	ds_read_b64 v[46:47], v119
	s_addc_u32 s29, s3, 0
	s_waitcnt lgkmcnt(0)
	v_pk_mul_f32 v[48:49], v[42:43], v[46:47] op_sel:[1,1] op_sel_hi:[1,0]
	s_nop 0
	v_pk_fma_f32 v[50:51], v[42:43], v[46:47], v[48:49] neg_lo:[0,0,1] neg_hi:[0,0,1]
	v_pk_fma_f32 v[42:43], v[42:43], v[46:47], v[48:49] op_sel_hi:[0,1,1]
	v_mov_b32_e32 v51, v43
	v_pk_add_f32 v[42:43], v[44:45], v[50:51]
	v_pk_add_f32 v[44:45], v[44:45], v[50:51] neg_lo:[0,1] neg_hi:[0,1]
	ds_read_b64 v[48:49], v72 offset:8192
	ds_read_b64 v[46:47], v80 offset:40960
	ds_read_b64 v[50:51], v120
	s_waitcnt lgkmcnt(0)
	v_pk_mul_f32 v[52:53], v[46:47], v[50:51] op_sel:[1,1] op_sel_hi:[1,0]
	s_nop 0
	v_pk_fma_f32 v[54:55], v[46:47], v[50:51], v[52:53] neg_lo:[0,0,1] neg_hi:[0,0,1]
	v_pk_fma_f32 v[46:47], v[46:47], v[50:51], v[52:53] op_sel_hi:[0,1,1]
	v_mov_b32_e32 v55, v47
	v_pk_add_f32 v[46:47], v[48:49], v[54:55]
	v_pk_add_f32 v[48:49], v[48:49], v[54:55] neg_lo:[0,1] neg_hi:[0,1]
	ds_read_b64 v[50:51], v73 offset:12288
	ds_read_b64 v[52:53], v81 offset:45056
	ds_read_b64 v[54:55], v121
	s_waitcnt lgkmcnt(0)
	v_pk_mul_f32 v[56:57], v[52:53], v[54:55] op_sel:[1,1] op_sel_hi:[1,0]
	s_nop 0
	v_pk_fma_f32 v[58:59], v[52:53], v[54:55], v[56:57] neg_lo:[0,0,1] neg_hi:[0,0,1]
	v_pk_fma_f32 v[52:53], v[52:53], v[54:55], v[56:57] op_sel_hi:[0,1,1]
	v_mov_b32_e32 v59, v53
	v_pk_add_f32 v[52:53], v[50:51], v[58:59]
	v_pk_add_f32 v[50:51], v[50:51], v[58:59] neg_lo:[0,1] neg_hi:[0,1]
	ds_read_b64 v[54:55], v74 offset:16384
	ds_read_b64 v[56:57], v82 offset:49152
	ds_read_b64 v[58:59], v122
	s_waitcnt lgkmcnt(0)
	v_pk_mul_f32 v[60:61], v[56:57], v[58:59] op_sel:[1,1] op_sel_hi:[1,0]
	s_nop 0
	v_pk_fma_f32 v[62:63], v[56:57], v[58:59], v[60:61] neg_lo:[0,0,1] neg_hi:[0,0,1]
	v_pk_fma_f32 v[56:57], v[56:57], v[58:59], v[60:61] op_sel_hi:[0,1,1]
	v_mov_b32_e32 v63, v57
	v_pk_add_f32 v[56:57], v[54:55], v[62:63]
	v_pk_add_f32 v[54:55], v[54:55], v[62:63] neg_lo:[0,1] neg_hi:[0,1]
	ds_read_b64 v[58:59], v75 offset:20480
	ds_read_b64 v[60:61], v83 offset:53248
	ds_read_b64 v[62:63], v123
	s_waitcnt lgkmcnt(0)
	v_pk_mul_f32 v[64:65], v[60:61], v[62:63] op_sel:[1,1] op_sel_hi:[1,0]
	s_nop 0
	v_pk_fma_f32 v[66:67], v[60:61], v[62:63], v[64:65] neg_lo:[0,0,1] neg_hi:[0,0,1]
	v_pk_fma_f32 v[60:61], v[60:61], v[62:63], v[64:65] op_sel_hi:[0,1,1]
	v_mov_b32_e32 v67, v61
	v_pk_add_f32 v[60:61], v[58:59], v[66:67]
	v_pk_add_f32 v[58:59], v[58:59], v[66:67] neg_lo:[0,1] neg_hi:[0,1]
	ds_read_b64 v[62:63], v76 offset:24576
	ds_read_b64 v[64:65], v84 offset:57344
	ds_read_b64 v[66:67], v124
	s_waitcnt lgkmcnt(0)
	v_pk_mul_f32 v[68:69], v[64:65], v[66:67] op_sel:[1,1] op_sel_hi:[1,0]
	s_nop 0
	v_pk_fma_f32 v[146:147], v[64:65], v[66:67], v[68:69] neg_lo:[0,0,1] neg_hi:[0,0,1]
	v_pk_fma_f32 v[64:65], v[64:65], v[66:67], v[68:69] op_sel_hi:[0,1,1]
	v_mov_b32_e32 v147, v65
	v_pk_add_f32 v[64:65], v[62:63], v[146:147]
	v_pk_add_f32 v[62:63], v[62:63], v[146:147] neg_lo:[0,1] neg_hi:[0,1]
	ds_read_b64 v[66:67], v77 offset:28672
	ds_read_b64 v[68:69], v85 offset:61440
	ds_read_b64 v[146:147], v125
	s_waitcnt lgkmcnt(0)
	s_barrier
	v_pk_mul_f32 v[148:149], v[68:69], v[146:147] op_sel:[1,1] op_sel_hi:[1,0]
	s_nop 0
	v_pk_fma_f32 v[150:151], v[68:69], v[146:147], v[148:149] neg_lo:[0,0,1] neg_hi:[0,0,1]
	v_pk_fma_f32 v[68:69], v[68:69], v[146:147], v[148:149] op_sel_hi:[0,1,1]
	v_mov_b32_e32 v151, v69
	v_pk_add_f32 v[68:69], v[66:67], v[150:151]
	v_pk_add_f32 v[66:67], v[66:67], v[150:151] neg_lo:[0,1] neg_hi:[0,1]
	ds_write_b64 v70, v[38:39]
	ds_write_b64 v78, v[40:41] offset:32768
	ds_write_b64 v71, v[42:43] offset:4096
	ds_write_b64 v79, v[44:45] offset:36864
	ds_write_b64 v72, v[46:47] offset:8192
	ds_write_b64 v80, v[48:49] offset:40960
	ds_write_b64 v73, v[52:53] offset:12288
	ds_write_b64 v81, v[50:51] offset:45056
	ds_write_b64 v74, v[56:57] offset:16384
	ds_write_b64 v82, v[54:55] offset:49152
	ds_write_b64 v75, v[60:61] offset:20480
	ds_write_b64 v83, v[58:59] offset:53248
	ds_write_b64 v76, v[64:65] offset:24576
	ds_write_b64 v84, v[62:63] offset:57344
	ds_write_b64 v77, v[68:69] offset:28672
	ds_write_b64 v85, v[66:67] offset:61440
	s_waitcnt lgkmcnt(0)
	s_barrier
	ds_read_b64 v[38:39], v70
	ds_read_b64 v[40:41], v126
	v_lshlrev_b64 v[42:43], 2, v[0:1]
	s_waitcnt lgkmcnt(0)
	v_pk_add_f32 v[38:39], v[38:39], v[40:41]
	s_nop 0
	v_mul_f32_e32 v38, 0.5, v38
	v_lshl_add_u64 v[40:41], s[2:3], 0, v[42:43]
	global_store_dword v[40:41], v38, off sc1
	v_mul_f32_e32 v44, 0.5, v39
	v_lshl_add_u64 v[38:39], s[28:29], 0, v[42:43]
	global_store_dword v[38:39], v44, off sc1
	ds_read_b64 v[42:43], v71 offset:4096
	ds_read_b64 v[44:45], v127
	s_waitcnt lgkmcnt(0)
	v_pk_add_f32 v[42:43], v[42:43], v[44:45]
	s_nop 0
	v_mul_f32_e32 v42, 0.5, v42
	global_store_dword v[40:41], v42, off offset:2048 sc1
	v_mul_f32_e32 v42, 0.5, v43
	global_store_dword v[38:39], v42, off offset:2048 sc1
	ds_read_b64 v[42:43], v72 offset:8192
	ds_read_b64 v[44:45], v128
	s_waitcnt lgkmcnt(0)
	v_pk_add_f32 v[42:43], v[42:43], v[44:45]
	v_add_co_u32_e32 v44, vcc, s34, v40
	v_mul_f32_e32 v42, 0.5, v42
	s_nop 0
	v_addc_co_u32_e32 v45, vcc, 0, v41, vcc
	v_add_co_u32_e32 v46, vcc, s15, v40
	v_mul_f32_e32 v50, 0.5, v43
	s_nop 0
	v_addc_co_u32_e32 v47, vcc, 0, v41, vcc
	global_store_dword v[46:47], v42, off offset:-4096 sc1
	v_add_co_u32_e32 v42, vcc, s34, v38
	s_nop 1
	v_addc_co_u32_e32 v43, vcc, 0, v39, vcc
	v_add_co_u32_e32 v48, vcc, s15, v38
	s_nop 1
	v_addc_co_u32_e32 v49, vcc, 0, v39, vcc
	global_store_dword v[48:49], v50, off offset:-4096 sc1
	ds_read_b64 v[50:51], v73 offset:12288
	ds_read_b64 v[52:53], v129
	s_waitcnt lgkmcnt(0)
	v_pk_add_f32 v[50:51], v[50:51], v[52:53]
	s_nop 0
	v_mul_f32_e32 v50, 0.5, v50
	global_store_dword v[44:45], v50, off offset:2048 sc1
	v_mul_f32_e32 v44, 0.5, v51
	global_store_dword v[42:43], v44, off offset:2048 sc1
	ds_read_b64 v[42:43], v74 offset:16384
	ds_read_b64 v[44:45], v130
	s_waitcnt lgkmcnt(0)
	v_pk_add_f32 v[42:43], v[42:43], v[44:45]
	s_nop 0
	v_mul_f32_e32 v42, 0.5, v42
	global_store_dword v[46:47], v42, off sc1
	v_mul_f32_e32 v42, 0.5, v43
	global_store_dword v[48:49], v42, off sc1
	ds_read_b64 v[42:43], v75 offset:20480
	ds_read_b64 v[44:45], v131
	s_waitcnt lgkmcnt(0)
	v_pk_add_f32 v[42:43], v[42:43], v[44:45]
	s_nop 0
	v_mul_f32_e32 v42, 0.5, v42
	global_store_dword v[46:47], v42, off offset:2048 sc1
	v_mul_f32_e32 v42, 0.5, v43
	global_store_dword v[48:49], v42, off offset:2048 sc1
	ds_read_b64 v[42:43], v76 offset:24576
	ds_read_b64 v[44:45], v132
	s_waitcnt lgkmcnt(0)
	v_pk_add_f32 v[42:43], v[42:43], v[44:45]
	v_add_co_u32_e32 v44, vcc, s35, v40
	v_mul_f32_e32 v42, 0.5, v42
	s_nop 0
	v_addc_co_u32_e32 v45, vcc, 0, v41, vcc
	v_add_co_u32_e32 v46, vcc, s44, v40
	v_mul_f32_e32 v50, 0.5, v43
	s_nop 0
	v_addc_co_u32_e32 v47, vcc, 0, v41, vcc
	global_store_dword v[46:47], v42, off offset:-4096 sc1
	v_add_co_u32_e32 v42, vcc, s35, v38
	s_nop 1
	v_addc_co_u32_e32 v43, vcc, 0, v39, vcc
	v_add_co_u32_e32 v48, vcc, s44, v38
	s_nop 1
	v_addc_co_u32_e32 v49, vcc, 0, v39, vcc
	global_store_dword v[48:49], v50, off offset:-4096 sc1
	ds_read_b64 v[50:51], v77 offset:28672
	ds_read_b64 v[52:53], v133
	s_waitcnt lgkmcnt(0)
	v_pk_add_f32 v[50:51], v[50:51], v[52:53]
	s_nop 0
	v_mul_f32_e32 v50, 0.5, v50
	global_store_dword v[44:45], v50, off offset:2048 sc1
	v_mul_f32_e32 v44, 0.5, v51
	global_store_dword v[42:43], v44, off offset:2048 sc1
	ds_read_b64 v[42:43], v78 offset:32768
	ds_read_b64 v[44:45], v134
	s_waitcnt lgkmcnt(0)
	v_pk_add_f32 v[42:43], v[42:43], v[44:45]
	s_nop 0
	v_mul_f32_e32 v42, 0.5, v42
	global_store_dword v[46:47], v42, off sc1
	v_mul_f32_e32 v42, 0.5, v43
	global_store_dword v[48:49], v42, off sc1
	ds_read_b64 v[42:43], v79 offset:36864
	ds_read_b64 v[44:45], v135
	s_waitcnt lgkmcnt(0)
	v_pk_add_f32 v[42:43], v[42:43], v[44:45]
	s_nop 0
	v_mul_f32_e32 v42, 0.5, v42
	global_store_dword v[46:47], v42, off offset:2048 sc1
	v_mul_f32_e32 v42, 0.5, v43
	global_store_dword v[48:49], v42, off offset:2048 sc1
	ds_read_b64 v[42:43], v80 offset:40960
	ds_read_b64 v[44:45], v136
	s_waitcnt lgkmcnt(0)
	v_pk_add_f32 v[42:43], v[42:43], v[44:45]
	v_add_co_u32_e32 v44, vcc, s46, v40
	v_mul_f32_e32 v42, 0.5, v42
	s_nop 0
	v_addc_co_u32_e32 v45, vcc, 0, v41, vcc
	v_add_co_u32_e32 v46, vcc, s45, v40
	v_mul_f32_e32 v50, 0.5, v43
	s_nop 0
	v_addc_co_u32_e32 v47, vcc, 0, v41, vcc
	global_store_dword v[46:47], v42, off offset:-4096 sc1
	v_add_co_u32_e32 v42, vcc, s46, v38
	s_nop 1
	v_addc_co_u32_e32 v43, vcc, 0, v39, vcc
	v_add_co_u32_e32 v48, vcc, s45, v38
	s_nop 1
	v_addc_co_u32_e32 v49, vcc, 0, v39, vcc
	global_store_dword v[48:49], v50, off offset:-4096 sc1
	ds_read_b64 v[50:51], v81 offset:45056
	ds_read_b64 v[52:53], v137
	v_add_co_u32_e32 v40, vcc, s59, v40
	s_waitcnt lgkmcnt(0)
	v_pk_add_f32 v[50:51], v[50:51], v[52:53]
	s_nop 0
	v_mul_f32_e32 v50, 0.5, v50
	global_store_dword v[44:45], v50, off offset:2048 sc1
	v_mul_f32_e32 v44, 0.5, v51
	global_store_dword v[42:43], v44, off offset:2048 sc1
	ds_read_b64 v[42:43], v82 offset:49152
	ds_read_b64 v[44:45], v138
	v_addc_co_u32_e32 v41, vcc, 0, v41, vcc
	v_add_co_u32_e32 v38, vcc, 0x7000, v38
	s_waitcnt lgkmcnt(0)
	v_pk_add_f32 v[42:43], v[42:43], v[44:45]
	v_addc_co_u32_e32 v39, vcc, 0, v39, vcc
	v_mul_f32_e32 v42, 0.5, v42
	global_store_dword v[46:47], v42, off sc1
	v_mul_f32_e32 v42, 0.5, v43
	global_store_dword v[48:49], v42, off sc1
	ds_read_b64 v[42:43], v83 offset:53248
	ds_read_b64 v[44:45], v139
	s_waitcnt lgkmcnt(0)
	v_pk_add_f32 v[42:43], v[42:43], v[44:45]
	s_nop 0
	v_mul_f32_e32 v42, 0.5, v42
	global_store_dword v[46:47], v42, off offset:2048 sc1
	v_mul_f32_e32 v42, 0.5, v43
	global_store_dword v[48:49], v42, off offset:2048 sc1
	ds_read_b64 v[42:43], v84 offset:57344
	ds_read_b64 v[44:45], v140
	s_waitcnt lgkmcnt(0)
	v_pk_add_f32 v[42:43], v[42:43], v[44:45]
	s_nop 0
	v_mul_f32_e32 v42, 0.5, v42
	global_store_dword v[40:41], v42, off sc1
	v_mul_f32_e32 v42, 0.5, v43
	global_store_dword v[38:39], v42, off sc1
	ds_read_b64 v[38:39], v85 offset:61440
	ds_read_b64 v[42:43], v141
	s_waitcnt lgkmcnt(0)
	v_pk_add_f32 v[38:39], v[38:39], v[42:43]
	s_nop 0
	v_mul_f32_e32 v38, 0.5, v38
	global_store_dword v[40:41], v38, off offset:2048 sc1
	v_mul_f32_e32 v38, 0.5, v39
	s_branch .LBB0_300
